# attention steady loops: the two LDS-DMA issues of a step moved into the first two PV gaps; m0 save/restore dropped
# baseline (speedup 1.0000x reference)
; #define WAIT_BAR(N) asm volatile("s_waitcnt vmcnt(" #N ") lgkmcnt(0)\n\ts_barrier":::"memory")
;   #define RESC() do{ if(!FIXREF&&resc){ asm volatile("s_waitcnt lgkmcnt(0)":::"memory"); \
;       _Pragma("unroll") for(int d_=0;d_<2;++d_) _Pragma("unroll") for(int r=0;r<16;++r)o[d_][r]*=wsf[crow(r,hi)]; } }while(0)
;   #define ROT() do{sl_prev=sl_cur;sl_cur=sl_next;sl_next=(sl_next==(NSLOT-1)*SLOTB)?0:sl_next+SLOTB;}while(0)
; template<int THRL,bool FIXREF,bool HALFK> __device__ __forceinline__ void attn_unit(float mref,long rowbase,int q0,const bf16*Qh,int PQ,const bf16*__restrict__ Kh_,int PK,const bf16*__restrict__ Vh_,int PV,bf16*Oh,int PO,const bf16*Gh,int PG,u32x4(&okeep)[4],int omode,float lam,float oml,const float ...
;     ...
;   int t=1;
;     ...
;   for(;t+5<NT;t+=2){
;     STEP(pB0,pB1,pA0,pA1,t,true,true,true);     WAIT_BAR(2); RESC(); ROT();
.LBB0_451:
	v_add_u32_e32 v0, s66, v227
	ds_read_b64_tr_b16 v[234:235], v0 offset:24576
	ds_read_b64_tr_b16 v[236:237], v0 offset:25088
	v_add_f32_e32 v102, v82, v83
	v_add_f32_e32 v102, v84, v102
	v_add_f32_e32 v102, v85, v102
	v_add_f32_e32 v102, v86, v102
	v_add_f32_e32 v102, v87, v102
	v_cvt_pk_bf16_f32 v166, v82, v83
	v_cvt_pk_bf16_f32 v167, v84, v85
	s_waitcnt lgkmcnt(9)
	v_mfma_f32_32x32x16_bf16 v[114:129], v[98:101], v[174:177], v[50:65]
	ds_read_b64_tr_b16 v[82:83], v0 offset:28672
	ds_read_b64_tr_b16 v[84:85], v0 offset:29184
	v_add_f32_e32 v98, v88, v102
	v_add_f32_e32 v98, v89, v98
	v_add_f32_e32 v98, v90, v98
	v_add_f32_e32 v146, v91, v98
	s_waitcnt lgkmcnt(10)
	v_mfma_f32_32x32x16_bf16 v[98:113], v[182:185], v[174:177], v[50:65]
	v_cvt_pk_bf16_f32 v168, v86, v87
	v_cvt_pk_bf16_f32 v169, v88, v89
	ds_read_b64_tr_b16 v[86:87], v0 offset:25600
	ds_read_b64_tr_b16 v[88:89], v0 offset:26112
	v_add_f32_e32 v146, v92, v146
	v_add_f32_e32 v146, v93, v146
	v_add_f32_e32 v146, v94, v146
	v_add_f32_e32 v146, v95, v146
	v_cvt_pk_bf16_f32 v158, v90, v91
	v_cvt_pk_bf16_f32 v159, v92, v93
	s_waitcnt lgkmcnt(11)
	v_mfma_f32_32x32x16_bf16 v[114:129], v[186:189], v[170:173], v[114:129]
	ds_read_b64_tr_b16 v[90:91], v0 offset:29696
	ds_read_b64_tr_b16 v[92:93], v0 offset:30208
	s_waitcnt lgkmcnt(12)
	v_mfma_f32_32x32x16_bf16 v[98:113], v[178:181], v[170:173], v[98:113]
	v_add_f32_e32 v146, v96, v146
	v_add_f32_e32 v146, v97, v146
	v_add_f32_e32 v146, v66, v146
	v_add_f32_e32 v146, v67, v146
	v_cvt_pk_bf16_f32 v160, v94, v95
	v_cvt_pk_bf16_f32 v161, v96, v97
	ds_read_b64_tr_b16 v[94:95], v0 offset:26624
	ds_read_b64_tr_b16 v[96:97], v0 offset:27136
	s_waitcnt lgkmcnt(13)
	v_mfma_f32_32x32x16_bf16 v[114:129], v[142:145], v[162:165], v[114:129]
	v_add_f32_e32 v142, v68, v146
	v_add_f32_e32 v142, v69, v142
	v_add_f32_e32 v142, v70, v142
	v_add_f32_e32 v142, v71, v142
	v_cvt_pk_bf16_f32 v150, v66, v67
	v_cvt_pk_bf16_f32 v151, v68, v69
	ds_read_b64_tr_b16 v[66:67], v0 offset:30720
	ds_read_b64_tr_b16 v[68:69], v0 offset:31232
	s_waitcnt lgkmcnt(14)
	v_mfma_f32_32x32x16_bf16 v[98:113], v[138:141], v[162:165], v[98:113]
	v_add_f32_e32 v138, v72, v142
	v_add_f32_e32 v138, v73, v138
	v_add_f32_e32 v138, v74, v138
	v_add_f32_e32 v138, v75, v138
	v_cvt_pk_bf16_f32 v152, v70, v71
	v_cvt_pk_bf16_f32 v153, v72, v73
	ds_read_b64_tr_b16 v[70:71], v0 offset:27648
	ds_read_b64_tr_b16 v[72:73], v0 offset:28160
	s_waitcnt lgkmcnt(14)
	v_mfma_f32_32x32x16_bf16 v[114:129], v[134:137], v[154:157], v[114:129]
	v_add_f32_e32 v134, v76, v138
	v_add_f32_e32 v134, v77, v134
	v_add_f32_e32 v134, v78, v134
	v_add_f32_e32 v134, v79, v134
	v_cvt_pk_bf16_f32 v146, v74, v75
	v_cvt_pk_bf16_f32 v147, v76, v77
	ds_read_b64_tr_b16 v[74:75], v0 offset:31744
	ds_read_b64_tr_b16 v[76:77], v0 offset:32256
	v_mfma_f32_32x32x16_bf16 v[98:113], v[130:133], v[154:157], v[98:113]
	v_add_f32_e32 v0, v80, v134
	v_add_f32_e32 v0, v81, v0
	v_add_f32_e32 v0, 0, v0
	v_cvt_pk_bf16_f32 v148, v78, v79
	v_cvt_pk_bf16_f32 v149, v80, v81
	v_add_f32_e32 v0, v232, v0
	s_waitcnt lgkmcnt(14)
	v_mfma_f32_32x32x16_bf16 v[18:33], v[166:169], v[234:237], v[18:33]
	v_exp_f32_e32 v114, v114
	v_exp_f32_e32 v115, v115
	v_exp_f32_e32 v116, v116
	v_exp_f32_e32 v117, v117
	v_lshl_add_u64 v[78:79], v[214:215], 0, s[12:13]
	s_add_i32 s40, s65, s62
	s_mov_b32 m0, s40
	s_nop 0
	global_load_lds_dwordx4 v[78:79], off
	s_waitcnt lgkmcnt(12)
	v_mfma_f32_32x32x16_bf16 v[34:49], v[166:169], v[82:85], v[34:49]
	v_exp_f32_e32 v118, v118
	v_exp_f32_e32 v119, v119
	v_exp_f32_e32 v120, v120
	v_exp_f32_e32 v121, v121
	v_lshl_add_u64 v[78:79], v[212:213], 0, s[22:23]
	s_add_i32 s40, s49, s61
	s_mov_b32 m0, s40
	s_nop 0
	global_load_lds_dwordx4 v[78:79], off
	v_add_u32_e32 v82, s49, v228
	ds_read_b128 v[78:81], v82
	ds_read_b128 v[134:137], v82 offset:512
	s_waitcnt lgkmcnt(12)
	v_mfma_f32_32x32x16_bf16 v[18:33], v[158:161], v[86:89], v[18:33]
	v_exp_f32_e32 v122, v122
	v_exp_f32_e32 v123, v123
	v_exp_f32_e32 v124, v124
	v_exp_f32_e32 v125, v125
	ds_read_b128 v[138:141], v82 offset:2048
	ds_read_b128 v[142:145], v82 offset:2560
	s_waitcnt lgkmcnt(12)
	v_mfma_f32_32x32x16_bf16 v[34:49], v[158:161], v[90:93], v[34:49]
	v_exp_f32_e32 v126, v126
	v_exp_f32_e32 v127, v127
	v_exp_f32_e32 v128, v128
	v_exp_f32_e32 v129, v129
	ds_read_b128 v[178:181], v82 offset:4096
	ds_read_b128 v[182:185], v82 offset:4608
	s_waitcnt lgkmcnt(12)
	v_mfma_f32_32x32x16_bf16 v[18:33], v[150:153], v[94:97], v[18:33]
	v_exp_f32_e32 v98, v98
	v_exp_f32_e32 v99, v99
	v_exp_f32_e32 v100, v100
	v_exp_f32_e32 v101, v101
	ds_read_b128 v[186:189], v82 offset:6144
	ds_read_b128 v[130:133], v82 offset:6656
	s_waitcnt lgkmcnt(12)
	v_mfma_f32_32x32x16_bf16 v[34:49], v[150:153], v[66:69], v[34:49]
	v_exp_f32_e32 v102, v102
	v_exp_f32_e32 v103, v103
	v_exp_f32_e32 v104, v104
	v_exp_f32_e32 v105, v105
	s_waitcnt lgkmcnt(10)
	v_mfma_f32_32x32x16_bf16 v[18:33], v[146:149], v[70:73], v[18:33]
	v_exp_f32_e32 v106, v106
	v_exp_f32_e32 v107, v107
	v_exp_f32_e32 v108, v108
	v_exp_f32_e32 v109, v109
	s_waitcnt lgkmcnt(8)
	v_mfma_f32_32x32x16_bf16 v[34:49], v[146:149], v[74:77], v[34:49]
	v_exp_f32_e32 v110, v110
	v_exp_f32_e32 v111, v111
	v_exp_f32_e32 v112, v112
	v_exp_f32_e32 v113, v113
	s_waitcnt vmcnt(2) lgkmcnt(0)
	s_barrier
; #define WAIT_BAR(N) asm volatile("s_waitcnt vmcnt(" #N ") lgkmcnt(0)\n\ts_barrier":::"memory")
;   #define RESC() do{ if(!FIXREF&&resc){ asm volatile("s_waitcnt lgkmcnt(0)":::"memory"); \
;       _Pragma("unroll") for(int d_=0;d_<2;++d_) _Pragma("unroll") for(int r=0;r<16;++r)o[d_][r]*=wsf[crow(r,hi)]; } }while(0)
;   #define ROT() do{sl_prev=sl_cur;sl_cur=sl_next;sl_next=(sl_next==(NSLOT-1)*SLOTB)?0:sl_next+SLOTB;}while(0)
; template<int THRL,bool FIXREF,bool HALFK> __device__ __forceinline__ void attn_unit(float mref,long rowbase,int q0,const bf16*Qh,int PQ,const bf16*__restrict__ Kh_,int PK,const bf16*__restrict__ Vh_,int PV,bf16*Oh,int PO,const bf16*Gh,int PG,u32x4(&okeep)[4],int omode,float lam,float oml,const float ...
;     ...
;   int t=1;
;     ...
;   for(;t+5<NT;t+=2){
;     STEP(pB0,pB1,pA0,pA1,t,true,true,true);     WAIT_BAR(2); RESC(); ROT();
;     STEP(pA0,pA1,pB0,pB1,t+1,true,true,true);   WAIT_BAR(2); RESC(); ROT();
	s_add_i32 s40, s49, 0x2000
	s_cmpk_lg_i32 s49, 0x4000
	s_cselect_b32 s40, s40, 0
	v_add_u32_e32 v232, s65, v227
	ds_read_b64_tr_b16 v[234:235], v232 offset:24576
	ds_read_b64_tr_b16 v[236:237], v232 offset:25088
	s_waitcnt lgkmcnt(9)
	v_mfma_f32_32x32x16_bf16 v[82:97], v[78:81], v[174:177], v[50:65]
	v_add_f32_e32 v66, v114, v115
	v_add_f32_e32 v66, v116, v66
	v_add_f32_e32 v66, v117, v66
	v_add_f32_e32 v66, v118, v66
	v_add_f32_e32 v66, v119, v66
	v_cvt_pk_bf16_f32 v166, v114, v115
	v_cvt_pk_bf16_f32 v167, v116, v117
	ds_read_b64_tr_b16 v[114:115], v232 offset:28672
	ds_read_b64_tr_b16 v[116:117], v232 offset:29184
	v_add_f32_e32 v66, v120, v66
	v_add_f32_e32 v66, v121, v66
	v_add_f32_e32 v66, v122, v66
	v_add_f32_e32 v146, v123, v66
	s_waitcnt lgkmcnt(10)
	v_mfma_f32_32x32x16_bf16 v[66:81], v[134:137], v[174:177], v[50:65]
	v_cvt_pk_bf16_f32 v168, v118, v119
	v_cvt_pk_bf16_f32 v169, v120, v121
	ds_read_b64_tr_b16 v[118:119], v232 offset:25600
	ds_read_b64_tr_b16 v[120:121], v232 offset:26112
	s_waitcnt lgkmcnt(11)
	v_mfma_f32_32x32x16_bf16 v[82:97], v[138:141], v[170:173], v[82:97]
	v_add_f32_e32 v134, v124, v146
	v_add_f32_e32 v134, v125, v134
	v_add_f32_e32 v134, v126, v134
	v_add_f32_e32 v134, v127, v134
	v_cvt_pk_bf16_f32 v158, v122, v123
	v_cvt_pk_bf16_f32 v159, v124, v125
	ds_read_b64_tr_b16 v[122:123], v232 offset:29696
	ds_read_b64_tr_b16 v[124:125], v232 offset:30208
	s_waitcnt lgkmcnt(12)
	v_mfma_f32_32x32x16_bf16 v[66:81], v[142:145], v[170:173], v[66:81]
	v_add_f32_e32 v134, v128, v134
	v_add_f32_e32 v134, v129, v134
	v_add_f32_e32 v134, v98, v134
	v_add_f32_e32 v134, v99, v134
	v_cvt_pk_bf16_f32 v160, v126, v127
	v_cvt_pk_bf16_f32 v161, v128, v129
	ds_read_b64_tr_b16 v[126:127], v232 offset:26624
	ds_read_b64_tr_b16 v[128:129], v232 offset:27136
	s_waitcnt lgkmcnt(13)
	v_mfma_f32_32x32x16_bf16 v[82:97], v[178:181], v[162:165], v[82:97]
	v_add_f32_e32 v134, v100, v134
	v_add_f32_e32 v134, v101, v134
	v_add_f32_e32 v134, v102, v134
	v_add_f32_e32 v134, v103, v134
	v_cvt_pk_bf16_f32 v150, v98, v99
	v_cvt_pk_bf16_f32 v151, v100, v101
	ds_read_b64_tr_b16 v[238:239], v232 offset:30720
	ds_read_b64_tr_b16 v[240:241], v232 offset:31232
	s_waitcnt lgkmcnt(14)
	v_mfma_f32_32x32x16_bf16 v[66:81], v[182:185], v[162:165], v[66:81]
	v_add_f32_e32 v98, v104, v134
	v_add_f32_e32 v98, v105, v98
	v_add_f32_e32 v98, v106, v98
	v_add_f32_e32 v98, v107, v98
	v_cvt_pk_bf16_f32 v152, v102, v103
	v_cvt_pk_bf16_f32 v153, v104, v105
	ds_read_b64_tr_b16 v[102:103], v232 offset:27648
	ds_read_b64_tr_b16 v[104:105], v232 offset:28160
	s_waitcnt lgkmcnt(14)
	v_mfma_f32_32x32x16_bf16 v[82:97], v[186:189], v[154:157], v[82:97]
	v_add_f32_e32 v98, v108, v98
	v_add_f32_e32 v98, v109, v98
	v_add_f32_e32 v98, v110, v98
	v_add_f32_e32 v98, v111, v98
	v_cvt_pk_bf16_f32 v146, v106, v107
	v_cvt_pk_bf16_f32 v147, v108, v109
	ds_read_b64_tr_b16 v[106:107], v232 offset:31744
	ds_read_b64_tr_b16 v[108:109], v232 offset:32256
	v_mfma_f32_32x32x16_bf16 v[66:81], v[130:133], v[154:157], v[66:81]
	v_add_f32_e32 v98, v112, v98
	v_add_f32_e32 v98, v113, v98
	v_add_f32_e32 v98, 0, v98
	v_cvt_pk_bf16_f32 v148, v110, v111
	v_cvt_pk_bf16_f32 v149, v112, v113
	s_nop 0
	v_add_f32_e32 v232, v0, v98
	s_waitcnt lgkmcnt(14)
	v_mfma_f32_32x32x16_bf16 v[18:33], v[166:169], v[234:237], v[18:33]
	v_exp_f32_e32 v82, v82
	v_exp_f32_e32 v83, v83
	v_exp_f32_e32 v84, v84
	v_exp_f32_e32 v85, v85
	v_lshl_add_u64 v[98:99], v[214:215], 0, s[92:93]
	s_add_i32 s41, s49, s62
	s_mov_b32 m0, s41
	s_nop 0
	global_load_lds_dwordx4 v[98:99], off
	s_waitcnt lgkmcnt(12)
	v_mfma_f32_32x32x16_bf16 v[34:49], v[166:169], v[114:117], v[34:49]
	v_exp_f32_e32 v86, v86
	v_exp_f32_e32 v87, v87
	v_exp_f32_e32 v88, v88
	v_exp_f32_e32 v89, v89
	v_lshl_add_u64 v[212:213], v[212:213], 0, s[4:5]
	s_add_i32 s41, s40, s61
	s_mov_b32 m0, s41
	s_nop 0
	global_load_lds_dwordx4 v[212:213], off
	v_add_u32_e32 v0, s40, v228
	ds_read_b128 v[98:101], v0
	ds_read_b128 v[182:185], v0 offset:512
	s_waitcnt lgkmcnt(12)
	v_mfma_f32_32x32x16_bf16 v[18:33], v[158:161], v[118:121], v[18:33]
	v_exp_f32_e32 v90, v90
	v_exp_f32_e32 v91, v91
	v_exp_f32_e32 v92, v92
	v_exp_f32_e32 v93, v93
	ds_read_b128 v[186:189], v0 offset:2048
	ds_read_b128 v[178:181], v0 offset:2560
	s_waitcnt lgkmcnt(12)
	v_mfma_f32_32x32x16_bf16 v[34:49], v[158:161], v[122:125], v[34:49]
	v_exp_f32_e32 v94, v94
	v_exp_f32_e32 v95, v95
	v_exp_f32_e32 v96, v96
	v_exp_f32_e32 v97, v97
	ds_read_b128 v[142:145], v0 offset:4096
	ds_read_b128 v[138:141], v0 offset:4608
	s_waitcnt lgkmcnt(12)
	v_mfma_f32_32x32x16_bf16 v[18:33], v[150:153], v[126:129], v[18:33]
	v_exp_f32_e32 v66, v66
	v_exp_f32_e32 v67, v67
	v_exp_f32_e32 v68, v68
	v_exp_f32_e32 v69, v69
	ds_read_b128 v[134:137], v0 offset:6144
	ds_read_b128 v[130:133], v0 offset:6656
	s_waitcnt lgkmcnt(12)
	v_mfma_f32_32x32x16_bf16 v[34:49], v[150:153], v[238:241], v[34:49]
	v_exp_f32_e32 v70, v70
	v_exp_f32_e32 v71, v71
	v_exp_f32_e32 v72, v72
	v_exp_f32_e32 v73, v73
	s_waitcnt lgkmcnt(10)
	v_mfma_f32_32x32x16_bf16 v[18:33], v[146:149], v[102:105], v[18:33]
	v_exp_f32_e32 v74, v74
	v_exp_f32_e32 v75, v75
	v_exp_f32_e32 v76, v76
	v_exp_f32_e32 v77, v77
	s_waitcnt lgkmcnt(8)
	v_mfma_f32_32x32x16_bf16 v[34:49], v[146:149], v[106:109], v[34:49]
	v_exp_f32_e32 v78, v78
	v_exp_f32_e32 v79, v79
	v_exp_f32_e32 v80, v80
	v_exp_f32_e32 v81, v81
	s_add_i32 s41, s40, 0x2000
	s_waitcnt vmcnt(2) lgkmcnt(0)
	s_barrier
	s_cmpk_lg_i32 s40, 0x4000
	s_mov_b32 s66, s49
	s_cselect_b32 s49, s41, 0
	s_add_i32 s48, s48, 2
	v_lshl_add_u64 v[214:215], v[214:215], 0, s[10:11]
	s_mov_b32 s65, s40
	s_cmp_gt_u32 s48, 56
	s_cbranch_scc0 .LBB0_451
;   #define RESC() do{ if(!FIXREF&&resc){ asm volatile("s_waitcnt lgkmcnt(0)":::"memory"); \
;       _Pragma("unroll") for(int d_=0;d_<2;++d_) _Pragma("unroll") for(int r=0;r<16;++r)o[d_][r]*=wsf[crow(r,hi)]; } }while(0)
;   #define ROT() do{sl_prev=sl_cur;sl_cur=sl_next;sl_next=(sl_next==(NSLOT-1)*SLOTB)?0:sl_next+SLOTB;}while(0)
;   #define ENDW(tt) do{ if((tt)+3<NT){WAIT_BAR(2);} else if((tt)+2<NT){WAIT_BAR(1);} else {WAIT_BAR(0);} }while(0)
; template<int THRL,bool FIXREF,bool HALFK> __device__ __forceinline__ void attn_unit(float mref,long rowbase,int q0,const bf16*Qh,int PQ,const bf16*__restrict__ Kh_,int PK,const bf16*__restrict__ Vh_,int PV,bf16*Oh,int PO,const bf16*Gh,int PG,u32x4(&okeep)[4],int omode,float lam,float oml,const float ...
;     ...
;   for(;t+1<NT;t+=2){
;     STEP(pB0,pB1,pA0,pA1,t,(t+3<NT),(t+1<NT),(t+1<NT));       ENDW(t);   RESC(); ROT();
	s_and_b32 s41, s64, 0x3fffffc0
	s_cmp_lg_u32 0, -1
	s_cselect_b32 s40, 0, 0
	s_add_i32 s42, s40, 0x6000
	v_add_u32_e32 v0, s42, v231
	s_lshl_b32 s41, s41, 2
	s_add_i32 s42, s41, 0
	v_add3_u32 v0, v0, v229, v230
	ds_read_b64_tr_b16 v[212:213], v227 offset:32768
	ds_read_b64_tr_b16 v[214:215], v227 offset:33280
	v_add_f32_e32 v102, v82, v83
	v_add_f32_e32 v102, v84, v102
	v_add_f32_e32 v102, v85, v102
	v_add_f32_e32 v102, v86, v102
	v_add_f32_e32 v102, v87, v102
	v_cvt_pk_bf16_f32 v166, v82, v83
	v_cvt_pk_bf16_f32 v167, v84, v85
	s_waitcnt lgkmcnt(9)
	v_mfma_f32_32x32x16_bf16 v[114:129], v[98:101], v[174:177], v[50:65]
	ds_read_b64_tr_b16 v[82:83], v227 offset:36864
	ds_read_b64_tr_b16 v[84:85], v227 offset:37376
	v_add_f32_e32 v98, v88, v102
	v_add_f32_e32 v98, v89, v98
	v_add_f32_e32 v98, v90, v98
	v_add_f32_e32 v146, v91, v98
	v_cvt_pk_bf16_f32 v168, v86, v87
	v_cvt_pk_bf16_f32 v169, v88, v89
	s_waitcnt lgkmcnt(10)
	v_mfma_f32_32x32x16_bf16 v[98:113], v[182:185], v[174:177], v[50:65]
	ds_read_b64_tr_b16 v[86:87], v227 offset:33792
	ds_read_b64_tr_b16 v[88:89], v227 offset:34304
	v_add_f32_e32 v146, v92, v146
	v_add_f32_e32 v146, v93, v146
	v_add_f32_e32 v146, v94, v146
	v_add_f32_e32 v146, v95, v146
	v_cvt_pk_bf16_f32 v158, v90, v91
	v_cvt_pk_bf16_f32 v159, v92, v93
	s_waitcnt lgkmcnt(11)
	v_mfma_f32_32x32x16_bf16 v[114:129], v[186:189], v[170:173], v[114:129]
	ds_read_b64_tr_b16 v[90:91], v227 offset:37888
	ds_read_b64_tr_b16 v[92:93], v227 offset:38400
	v_add_f32_e32 v146, v96, v146
	v_add_f32_e32 v146, v97, v146
	v_add_f32_e32 v146, v66, v146
	v_add_f32_e32 v146, v67, v146
	v_cvt_pk_bf16_f32 v160, v94, v95
	v_cvt_pk_bf16_f32 v161, v96, v97
	s_waitcnt lgkmcnt(12)
	v_mfma_f32_32x32x16_bf16 v[98:113], v[178:181], v[170:173], v[98:113]
	ds_read_b64_tr_b16 v[94:95], v227 offset:34816
	ds_read_b64_tr_b16 v[96:97], v227 offset:35328
	s_waitcnt lgkmcnt(13)
	v_mfma_f32_32x32x16_bf16 v[114:129], v[142:145], v[162:165], v[114:129]
	v_add_f32_e32 v142, v68, v146
	v_add_f32_e32 v142, v69, v142
	v_add_f32_e32 v142, v70, v142
	v_add_f32_e32 v142, v71, v142
	v_cvt_pk_bf16_f32 v150, v66, v67
	v_cvt_pk_bf16_f32 v151, v68, v69
	ds_read_b64_tr_b16 v[66:67], v227 offset:38912
	ds_read_b64_tr_b16 v[68:69], v227 offset:39424
	s_waitcnt lgkmcnt(14)
	v_mfma_f32_32x32x16_bf16 v[98:113], v[138:141], v[162:165], v[98:113]
	v_add_f32_e32 v138, v72, v142
	v_add_f32_e32 v138, v73, v138
	v_add_f32_e32 v138, v74, v138
	v_add_f32_e32 v138, v75, v138
	v_cvt_pk_bf16_f32 v152, v70, v71
	v_cvt_pk_bf16_f32 v153, v72, v73
	ds_read_b64_tr_b16 v[70:71], v227 offset:35840
	ds_read_b64_tr_b16 v[72:73], v227 offset:36352
	s_waitcnt lgkmcnt(14)
	v_mfma_f32_32x32x16_bf16 v[114:129], v[134:137], v[154:157], v[114:129]
	v_add_f32_e32 v134, v76, v138
	v_add_f32_e32 v134, v77, v134
	v_add_f32_e32 v134, v78, v134
	v_add_f32_e32 v134, v79, v134
	v_cvt_pk_bf16_f32 v146, v74, v75
	v_cvt_pk_bf16_f32 v147, v76, v77
	ds_read_b64_tr_b16 v[74:75], v227 offset:39936
	ds_read_b64_tr_b16 v[76:77], v227 offset:40448
	v_mfma_f32_32x32x16_bf16 v[98:113], v[130:133], v[154:157], v[98:113]
	v_add_f32_e32 v130, v80, v134
	v_add_f32_e32 v130, v81, v130
	v_add_f32_e32 v130, 0, v130
	v_cvt_pk_bf16_f32 v148, v78, v79
	v_cvt_pk_bf16_f32 v149, v80, v81
	s_mov_b64 s[46:47], 0xf8000
	s_add_i32 s40, s40, s63
	v_lshl_add_u64 v[78:79], v[210:211], 0, s[46:47]
	s_add_i32 s41, s40, 0x4000
	s_mov_b32 s43, m0
	s_mov_b32 m0, s41
	s_nop 0
	global_load_lds_dwordx4 v[78:79], off
	s_mov_b32 m0, s43
	v_lshl_add_u64 v[78:79], v[208:209], 0, s[18:19]
	s_mov_b32 s41, m0
	s_mov_b32 m0, s61
	s_nop 0
	global_load_lds_dwordx4 v[78:79], off
	s_mov_b32 m0, s41
	v_add_f32_e32 v229, v232, v130
	s_waitcnt lgkmcnt(14)
	v_mfma_f32_32x32x16_bf16 v[18:33], v[166:169], v[212:215], v[18:33]
	v_exp_f32_e32 v114, v114
	v_exp_f32_e32 v115, v115
	v_exp_f32_e32 v116, v116
	v_exp_f32_e32 v117, v117
	s_waitcnt lgkmcnt(12)
	v_mfma_f32_32x32x16_bf16 v[34:49], v[166:169], v[82:85], v[34:49]
	v_exp_f32_e32 v118, v118
	v_exp_f32_e32 v119, v119
	v_exp_f32_e32 v120, v120
	v_exp_f32_e32 v121, v121
	ds_read_b128 v[78:81], v228
	ds_read_b128 v[178:181], v228 offset:512
	s_waitcnt lgkmcnt(12)
	v_mfma_f32_32x32x16_bf16 v[18:33], v[158:161], v[86:89], v[18:33]
	v_exp_f32_e32 v122, v122
	v_exp_f32_e32 v123, v123
	v_exp_f32_e32 v124, v124
	v_exp_f32_e32 v125, v125
	ds_read_b128 v[86:89], v228 offset:2048
	ds_read_b128 v[182:185], v228 offset:2560
	s_waitcnt lgkmcnt(12)
	v_mfma_f32_32x32x16_bf16 v[34:49], v[158:161], v[90:93], v[34:49]
	v_exp_f32_e32 v126, v126
	v_exp_f32_e32 v127, v127
	v_exp_f32_e32 v128, v128
	v_exp_f32_e32 v129, v129
	ds_read_b128 v[90:93], v228 offset:4096
	ds_read_b128 v[186:189], v228 offset:4608
	s_waitcnt lgkmcnt(12)
	v_mfma_f32_32x32x16_bf16 v[18:33], v[150:153], v[94:97], v[18:33]
	v_exp_f32_e32 v98, v98
	v_exp_f32_e32 v99, v99
	v_exp_f32_e32 v100, v100
	v_exp_f32_e32 v101, v101
	ds_read_b128 v[94:97], v228 offset:6144
	ds_read_b128 v[82:85], v228 offset:6656
	s_waitcnt lgkmcnt(12)
	v_mfma_f32_32x32x16_bf16 v[34:49], v[150:153], v[66:69], v[34:49]
	v_exp_f32_e32 v102, v102
	v_exp_f32_e32 v103, v103
	v_exp_f32_e32 v104, v104
	v_exp_f32_e32 v105, v105
	s_waitcnt lgkmcnt(10)
	v_mfma_f32_32x32x16_bf16 v[18:33], v[146:149], v[70:73], v[18:33]
	v_exp_f32_e32 v106, v106
	v_exp_f32_e32 v107, v107
	v_exp_f32_e32 v108, v108
	v_exp_f32_e32 v109, v109
	s_waitcnt lgkmcnt(8)
	v_mfma_f32_32x32x16_bf16 v[34:49], v[146:149], v[74:77], v[34:49]
	v_exp_f32_e32 v110, v110
	v_exp_f32_e32 v111, v111
	v_exp_f32_e32 v112, v112
	v_exp_f32_e32 v113, v113
	s_waitcnt vmcnt(2) lgkmcnt(0)
	s_barrier
;   #define RESC() do{ if(!FIXREF&&resc){ asm volatile("s_waitcnt lgkmcnt(0)":::"memory"); \
;       _Pragma("unroll") for(int d_=0;d_<2;++d_) _Pragma("unroll") for(int r=0;r<16;++r)o[d_][r]*=wsf[crow(r,hi)]; } }while(0)
;   #define ROT() do{sl_prev=sl_cur;sl_cur=sl_next;sl_next=(sl_next==(NSLOT-1)*SLOTB)?0:sl_next+SLOTB;}while(0)
;   #define ENDW(tt) do{ if((tt)+3<NT){WAIT_BAR(2);} else if((tt)+2<NT){WAIT_BAR(1);} else {WAIT_BAR(0);} }while(0)
; template<int THRL,bool FIXREF,bool HALFK> __device__ __forceinline__ void attn_unit(float mref,long rowbase,int q0,const bf16*Qh,int PQ,const bf16*__restrict__ Kh_,int PK,const bf16*__restrict__ Vh_,int PV,bf16*Oh,int PO,const bf16*Gh,int PG,u32x4(&okeep)[4],int omode,float lam,float oml,const float ...
;     ...
;     STEP(pA0,pA1,pB0,pB1,t+1,(t+4<NT),(t+2<NT),(t+2<NT));     ENDW(t+1); RESC(); ROT();
	ds_read_b64_tr_b16 v[212:213], v227 offset:40960
	ds_read_b64_tr_b16 v[214:215], v227 offset:41472
	v_add_f32_e32 v66, v114, v115
	v_add_f32_e32 v66, v116, v66
	v_add_f32_e32 v66, v117, v66
	v_add_f32_e32 v66, v118, v66
	v_add_f32_e32 v66, v119, v66
	v_cvt_pk_bf16_f32 v166, v114, v115
	v_cvt_pk_bf16_f32 v167, v116, v117
	s_waitcnt lgkmcnt(9)
	v_mfma_f32_32x32x16_bf16 v[130:145], v[78:81], v[174:177], v[50:65]
	ds_read_b64_tr_b16 v[114:115], v227 offset:45056
	ds_read_b64_tr_b16 v[116:117], v227 offset:45568
	v_add_f32_e32 v66, v120, v66
	v_add_f32_e32 v66, v121, v66
	v_add_f32_e32 v66, v122, v66
	v_add_f32_e32 v146, v123, v66
	s_waitcnt lgkmcnt(10)
	v_mfma_f32_32x32x16_bf16 v[66:81], v[178:181], v[174:177], v[50:65]
	v_cvt_pk_bf16_f32 v168, v118, v119
	v_cvt_pk_bf16_f32 v169, v120, v121
	ds_read_b64_tr_b16 v[118:119], v227 offset:41984
	ds_read_b64_tr_b16 v[120:121], v227 offset:42496
	s_waitcnt lgkmcnt(11)
	v_mfma_f32_32x32x16_bf16 v[130:145], v[86:89], v[170:173], v[130:145]
	v_add_f32_e32 v86, v124, v146
	v_add_f32_e32 v86, v125, v86
	v_add_f32_e32 v86, v126, v86
	v_add_f32_e32 v146, v127, v86
	v_cvt_pk_bf16_f32 v158, v122, v123
	v_cvt_pk_bf16_f32 v159, v124, v125
	ds_read_b64_tr_b16 v[86:87], v227 offset:46080
	ds_read_b64_tr_b16 v[88:89], v227 offset:46592
	s_waitcnt lgkmcnt(12)
	v_mfma_f32_32x32x16_bf16 v[66:81], v[182:185], v[170:173], v[66:81]
	v_add_f32_e32 v122, v128, v146
	v_add_f32_e32 v122, v129, v122
	v_add_f32_e32 v122, v98, v122
	v_add_f32_e32 v146, v99, v122
	v_cvt_pk_bf16_f32 v160, v126, v127
	v_cvt_pk_bf16_f32 v161, v128, v129
	ds_read_b64_tr_b16 v[122:123], v227 offset:43008
	ds_read_b64_tr_b16 v[124:125], v227 offset:43520
	s_waitcnt lgkmcnt(13)
	v_mfma_f32_32x32x16_bf16 v[130:145], v[90:93], v[162:165], v[130:145]
	v_add_f32_e32 v90, v100, v146
	v_add_f32_e32 v90, v101, v90
	v_add_f32_e32 v90, v102, v90
	v_add_f32_e32 v126, v103, v90
	v_cvt_pk_bf16_f32 v150, v98, v99
	v_cvt_pk_bf16_f32 v151, v100, v101
	ds_read_b64_tr_b16 v[90:91], v227 offset:47104
	ds_read_b64_tr_b16 v[92:93], v227 offset:47616
	s_waitcnt lgkmcnt(14)
	v_mfma_f32_32x32x16_bf16 v[66:81], v[186:189], v[162:165], v[66:81]
	v_add_f32_e32 v98, v104, v126
	v_add_f32_e32 v98, v105, v98
	v_add_f32_e32 v98, v106, v98
	v_add_f32_e32 v98, v107, v98
	v_cvt_pk_bf16_f32 v152, v102, v103
	v_cvt_pk_bf16_f32 v153, v104, v105
	ds_read_b64_tr_b16 v[102:103], v227 offset:44032
	ds_read_b64_tr_b16 v[104:105], v227 offset:44544
	s_waitcnt lgkmcnt(14)
	v_mfma_f32_32x32x16_bf16 v[130:145], v[94:97], v[154:157], v[130:145]
	v_add_f32_e32 v94, v108, v98
	v_add_f32_e32 v94, v109, v94
	v_add_f32_e32 v94, v110, v94
	v_add_f32_e32 v98, v111, v94
	v_cvt_pk_bf16_f32 v146, v106, v107
	v_cvt_pk_bf16_f32 v147, v108, v109
	ds_read_b64_tr_b16 v[94:95], v227 offset:48128
	ds_read_b64_tr_b16 v[96:97], v227 offset:48640
	v_mfma_f32_32x32x16_bf16 v[66:81], v[82:85], v[154:157], v[66:81]
	v_add_f32_e32 v82, v112, v98
	v_add_f32_e32 v82, v113, v82
	v_add_f32_e32 v82, 0, v82
	v_cvt_pk_bf16_f32 v148, v110, v111
	v_cvt_pk_bf16_f32 v149, v112, v113
	s_mov_b64 s[46:47], 0xfc000
	v_add_f32_e32 v229, v229, v82
	v_lshl_add_u64 v[82:83], v[210:211], 0, s[46:47]
	s_mov_b32 s41, m0
	s_mov_b32 m0, s62
	s_nop 0
	global_load_lds_dwordx4 v[82:83], off
	s_mov_b32 m0, s41
	v_lshl_add_u64 v[82:83], v[208:209], 0, s[6:7]
	s_add_i32 s41, s40, 0x8000
	s_mov_b32 s43, m0
	s_mov_b32 m0, s41
	s_nop 0
	global_load_lds_dwordx4 v[82:83], off
	s_mov_b32 m0, s43
	s_waitcnt lgkmcnt(14)
	v_mfma_f32_32x32x16_bf16 v[18:33], v[166:169], v[212:215], v[18:33]
	v_exp_f32_e32 v130, v130
	v_exp_f32_e32 v131, v131
	v_exp_f32_e32 v132, v132
	v_exp_f32_e32 v133, v133
	s_waitcnt lgkmcnt(12)
	v_mfma_f32_32x32x16_bf16 v[34:49], v[166:169], v[114:117], v[34:49]
	v_exp_f32_e32 v134, v134
	v_exp_f32_e32 v135, v135
	v_exp_f32_e32 v136, v136
	v_exp_f32_e32 v137, v137
	ds_read_b128 v[82:85], v228 offset:8192
	ds_read_b128 v[106:109], v228 offset:8704
	s_waitcnt lgkmcnt(12)
	v_mfma_f32_32x32x16_bf16 v[18:33], v[158:161], v[118:121], v[18:33]
	v_exp_f32_e32 v138, v138
	v_exp_f32_e32 v139, v139
	v_exp_f32_e32 v140, v140
	v_exp_f32_e32 v141, v141
	ds_read_b128 v[110:113], v228 offset:10240
	ds_read_b128 v[178:181], v228 offset:10752
	s_waitcnt lgkmcnt(12)
	v_mfma_f32_32x32x16_bf16 v[34:49], v[158:161], v[86:89], v[34:49]
	v_exp_f32_e32 v142, v142
	v_exp_f32_e32 v143, v143
	v_exp_f32_e32 v144, v144
	v_exp_f32_e32 v145, v145
	ds_read_b128 v[182:185], v228 offset:12288
	ds_read_b128 v[186:189], v228 offset:12800
	s_waitcnt lgkmcnt(12)
	v_mfma_f32_32x32x16_bf16 v[18:33], v[150:153], v[122:125], v[18:33]
	v_exp_f32_e32 v66, v66
	v_exp_f32_e32 v67, v67
	v_exp_f32_e32 v68, v68
	v_exp_f32_e32 v69, v69
	ds_read_b128 v[210:213], v228 offset:14336
	ds_read_b128 v[98:101], v228 offset:14848
	s_waitcnt lgkmcnt(12)
	v_mfma_f32_32x32x16_bf16 v[34:49], v[150:153], v[90:93], v[34:49]
	v_exp_f32_e32 v70, v70
	v_exp_f32_e32 v71, v71
	v_exp_f32_e32 v72, v72
	v_exp_f32_e32 v73, v73
	s_waitcnt lgkmcnt(10)
	v_mfma_f32_32x32x16_bf16 v[18:33], v[146:149], v[102:105], v[18:33]
	v_exp_f32_e32 v74, v74
	v_exp_f32_e32 v75, v75
	v_exp_f32_e32 v76, v76
	v_exp_f32_e32 v77, v77
	s_waitcnt lgkmcnt(8)
	v_mfma_f32_32x32x16_bf16 v[34:49], v[146:149], v[94:97], v[34:49]
	v_exp_f32_e32 v78, v78
	v_exp_f32_e32 v79, v79
	v_exp_f32_e32 v80, v80
	v_exp_f32_e32 v81, v81
	s_waitcnt vmcnt(2) lgkmcnt(0)
	s_barrier
;   #define RESC() do{ if(!FIXREF&&resc){ asm volatile("s_waitcnt lgkmcnt(0)":::"memory"); \
;       _Pragma("unroll") for(int d_=0;d_<2;++d_) _Pragma("unroll") for(int r=0;r<16;++r)o[d_][r]*=wsf[crow(r,hi)]; } }while(0)
;   #define ROT() do{sl_prev=sl_cur;sl_cur=sl_next;sl_next=(sl_next==(NSLOT-1)*SLOTB)?0:sl_next+SLOTB;}while(0)
;   #define ENDW(tt) do{ if((tt)+3<NT){WAIT_BAR(2);} else if((tt)+2<NT){WAIT_BAR(1);} else {WAIT_BAR(0);} }while(0)
; template<int THRL,bool FIXREF,bool HALFK> __device__ __forceinline__ void attn_unit(float mref,long rowbase,int q0,const bf16*Qh,int PQ,const bf16*__restrict__ Kh_,int PK,const bf16*__restrict__ Vh_,int PV,bf16*Oh,int PO,const bf16*Gh,int PG,u32x4(&okeep)[4],int omode,float lam,float oml,const float ...
;     ...
;     STEP(pA0,pA1,pB0,pB1,t+1,(t+4<NT),(t+2<NT),(t+2<NT));     ENDW(t+1); RESC(); ROT();
	ds_read_b64_tr_b16 v[102:103], v227 offset:24576
	ds_read_b64_tr_b16 v[104:105], v227 offset:25088
	v_add_f32_e32 v86, v130, v131
	v_add_f32_e32 v86, v132, v86
	v_add_f32_e32 v86, v133, v86
	v_add_f32_e32 v86, v134, v86
	v_add_f32_e32 v86, v135, v86
	v_cvt_pk_bf16_f32 v166, v130, v131
	v_cvt_pk_bf16_f32 v167, v132, v133
	s_waitcnt lgkmcnt(9)
	v_mfma_f32_32x32x16_bf16 v[114:129], v[82:85], v[174:177], v[50:65]
	ds_read_b64_tr_b16 v[130:131], v227 offset:28672
	ds_read_b64_tr_b16 v[132:133], v227 offset:29184
	v_add_f32_e32 v82, v136, v86
	v_add_f32_e32 v82, v137, v82
	v_add_f32_e32 v82, v138, v82
	v_add_f32_e32 v146, v139, v82
	v_cvt_pk_bf16_f32 v168, v134, v135
	v_cvt_pk_bf16_f32 v169, v136, v137
	s_waitcnt lgkmcnt(10)
	v_mfma_f32_32x32x16_bf16 v[82:97], v[106:109], v[174:177], v[50:65]
	ds_read_b64_tr_b16 v[106:107], v227 offset:25600
	ds_read_b64_tr_b16 v[108:109], v227 offset:26112
	s_waitcnt lgkmcnt(11)
	v_mfma_f32_32x32x16_bf16 v[114:129], v[110:113], v[170:173], v[114:129]
	v_add_f32_e32 v110, v140, v146
	v_add_f32_e32 v110, v141, v110
	v_add_f32_e32 v110, v142, v110
	v_add_f32_e32 v134, v143, v110
	v_cvt_pk_bf16_f32 v158, v138, v139
	v_cvt_pk_bf16_f32 v159, v140, v141
	ds_read_b64_tr_b16 v[110:111], v227 offset:29696
	ds_read_b64_tr_b16 v[112:113], v227 offset:30208
	v_add_f32_e32 v134, v144, v134
	v_add_f32_e32 v134, v145, v134
	v_add_f32_e32 v134, v66, v134
	v_add_f32_e32 v138, v67, v134
	v_cvt_pk_bf16_f32 v160, v142, v143
	v_cvt_pk_bf16_f32 v161, v144, v145
	s_waitcnt lgkmcnt(12)
	v_mfma_f32_32x32x16_bf16 v[82:97], v[178:181], v[170:173], v[82:97]
	ds_read_b64_tr_b16 v[134:135], v227 offset:26624
	ds_read_b64_tr_b16 v[136:137], v227 offset:27136
	v_add_f32_e32 v138, v68, v138
	v_add_f32_e32 v138, v69, v138
	v_add_f32_e32 v138, v70, v138
	v_add_f32_e32 v138, v71, v138
	v_cvt_pk_bf16_f32 v150, v66, v67
	v_cvt_pk_bf16_f32 v151, v68, v69
	s_waitcnt lgkmcnt(13)
	v_mfma_f32_32x32x16_bf16 v[114:129], v[182:185], v[162:165], v[114:129]
	ds_read_b64_tr_b16 v[66:67], v227 offset:30720
	ds_read_b64_tr_b16 v[68:69], v227 offset:31232
	v_add_f32_e32 v138, v72, v138
	v_add_f32_e32 v138, v73, v138
	v_add_f32_e32 v138, v74, v138
	v_add_f32_e32 v138, v75, v138
	v_cvt_pk_bf16_f32 v152, v70, v71
	v_cvt_pk_bf16_f32 v153, v72, v73
	s_waitcnt lgkmcnt(14)
	v_mfma_f32_32x32x16_bf16 v[82:97], v[186:189], v[162:165], v[82:97]
	ds_read_b64_tr_b16 v[70:71], v227 offset:27648
	ds_read_b64_tr_b16 v[72:73], v227 offset:28160
	v_add_f32_e32 v138, v76, v138
	v_add_f32_e32 v138, v77, v138
	v_add_f32_e32 v138, v78, v138
	v_add_f32_e32 v138, v79, v138
	v_cvt_pk_bf16_f32 v146, v74, v75
	v_cvt_pk_bf16_f32 v147, v76, v77
	s_waitcnt lgkmcnt(14)
	v_mfma_f32_32x32x16_bf16 v[114:129], v[210:213], v[154:157], v[114:129]
	ds_read_b64_tr_b16 v[74:75], v227 offset:31744
	ds_read_b64_tr_b16 v[76:77], v227 offset:32256
	v_mfma_f32_32x32x16_bf16 v[82:97], v[98:101], v[154:157], v[82:97]
	v_add_f32_e32 v98, v80, v138
	v_add_f32_e32 v98, v81, v98
	v_add_f32_e32 v98, 0, v98
	v_cvt_pk_bf16_f32 v148, v78, v79
	v_cvt_pk_bf16_f32 v149, v80, v81
	v_lshl_add_u64 v[78:79], v[208:209], 0, s[94:95]
	s_add_i32 s40, s40, 0xa000
	s_mov_b32 s41, m0
	s_mov_b32 m0, s40
	s_nop 0
	global_load_lds_dwordx4 v[78:79], off
	s_mov_b32 m0, s41
	v_add_f32_e32 v214, v229, v98
	s_waitcnt lgkmcnt(14)
	v_mfma_f32_32x32x16_bf16 v[18:33], v[166:169], v[102:105], v[18:33]
	v_exp_f32_e32 v114, v114
	v_exp_f32_e32 v115, v115
	v_exp_f32_e32 v116, v116
	v_exp_f32_e32 v117, v117
	s_waitcnt lgkmcnt(12)
	v_mfma_f32_32x32x16_bf16 v[34:49], v[166:169], v[130:133], v[34:49]
	v_exp_f32_e32 v118, v118
	v_exp_f32_e32 v119, v119
	v_exp_f32_e32 v120, v120
	v_exp_f32_e32 v121, v121
	ds_read_b128 v[78:81], v228 offset:16384
	ds_read_b128 v[138:141], v228 offset:16896
	s_waitcnt lgkmcnt(12)
	v_mfma_f32_32x32x16_bf16 v[18:33], v[158:161], v[106:109], v[18:33]
	v_exp_f32_e32 v122, v122
	v_exp_f32_e32 v123, v123
	v_exp_f32_e32 v124, v124
	v_exp_f32_e32 v125, v125
	ds_read_b128 v[142:145], v228 offset:18432
	ds_read_b128 v[178:181], v228 offset:18944
	s_waitcnt lgkmcnt(12)
	v_mfma_f32_32x32x16_bf16 v[34:49], v[158:161], v[110:113], v[34:49]
	v_exp_f32_e32 v126, v126
	v_exp_f32_e32 v127, v127
	v_exp_f32_e32 v128, v128
	v_exp_f32_e32 v129, v129
	ds_read_b128 v[182:185], v228 offset:20480
	ds_read_b128 v[186:189], v228 offset:20992
	s_waitcnt lgkmcnt(12)
	v_mfma_f32_32x32x16_bf16 v[18:33], v[150:153], v[134:137], v[18:33]
	v_exp_f32_e32 v82, v82
	v_exp_f32_e32 v83, v83
	v_exp_f32_e32 v84, v84
	v_exp_f32_e32 v85, v85
	ds_read_b128 v[134:137], v228 offset:22528
	ds_read_b128 v[130:133], v228 offset:23040
	s_waitcnt lgkmcnt(12)
	v_mfma_f32_32x32x16_bf16 v[34:49], v[150:153], v[66:69], v[34:49]
	v_exp_f32_e32 v86, v86
	v_exp_f32_e32 v87, v87
	v_exp_f32_e32 v88, v88
	v_exp_f32_e32 v89, v89
	s_waitcnt lgkmcnt(10)
	v_mfma_f32_32x32x16_bf16 v[18:33], v[146:149], v[70:73], v[18:33]
	v_exp_f32_e32 v90, v90
	v_exp_f32_e32 v91, v91
	v_exp_f32_e32 v92, v92
	v_exp_f32_e32 v93, v93
	s_waitcnt lgkmcnt(8)
	v_mfma_f32_32x32x16_bf16 v[34:49], v[146:149], v[74:77], v[34:49]
	v_exp_f32_e32 v94, v94
	v_exp_f32_e32 v95, v95
	v_exp_f32_e32 v96, v96
	v_exp_f32_e32 v97, v97
	s_waitcnt vmcnt(1) lgkmcnt(0)
	s_barrier
;   #define RESC() do{ if(!FIXREF&&resc){ asm volatile("s_waitcnt lgkmcnt(0)":::"memory"); \
;       _Pragma("unroll") for(int d_=0;d_<2;++d_) _Pragma("unroll") for(int r=0;r<16;++r)o[d_][r]*=wsf[crow(r,hi)]; } }while(0)
;   #define ROT() do{sl_prev=sl_cur;sl_cur=sl_next;sl_next=(sl_next==(NSLOT-1)*SLOTB)?0:sl_next+SLOTB;}while(0)
;   #define ENDW(tt) do{ if((tt)+3<NT){WAIT_BAR(2);} else if((tt)+2<NT){WAIT_BAR(1);} else {WAIT_BAR(0);} }while(0)
; template<int THRL,bool FIXREF,bool HALFK> __device__ __forceinline__ void attn_unit(float mref,long rowbase,int q0,const bf16*Qh,int PQ,const bf16*__restrict__ Kh_,int PK,const bf16*__restrict__ Vh_,int PV,bf16*Oh,int PO,const bf16*Gh,int PG,u32x4(&okeep)[4],int omode,float lam,float oml,const float ...
;     ...
;     STEP(pA0,pA1,pB0,pB1,t+1,(t+4<NT),(t+2<NT),(t+2<NT));     ENDW(t+1); RESC(); ROT();
	ds_read_b64_tr_b16 v[210:211], v227 offset:32768
	ds_read_b64_tr_b16 v[212:213], v227 offset:33280
	v_add_f32_e32 v66, v114, v115
	v_add_f32_e32 v66, v116, v66
	v_add_f32_e32 v66, v117, v66
	v_add_f32_e32 v66, v118, v66
	v_add_f32_e32 v66, v119, v66
	v_cvt_pk_bf16_f32 v166, v114, v115
	v_cvt_pk_bf16_f32 v167, v116, v117
	s_waitcnt lgkmcnt(9)
	v_mfma_f32_32x32x16_bf16 v[98:113], v[78:81], v[174:177], v[50:65]
	ds_read_b64_tr_b16 v[114:115], v227 offset:36864
	ds_read_b64_tr_b16 v[116:117], v227 offset:37376
	v_add_f32_e32 v66, v120, v66
	v_add_f32_e32 v66, v121, v66
	v_add_f32_e32 v66, v122, v66
	v_add_f32_e32 v146, v123, v66
	s_waitcnt lgkmcnt(10)
	v_mfma_f32_32x32x16_bf16 v[66:81], v[138:141], v[174:177], v[50:65]
	v_cvt_pk_bf16_f32 v168, v118, v119
	v_cvt_pk_bf16_f32 v169, v120, v121
	ds_read_b64_tr_b16 v[138:139], v227 offset:33792
	ds_read_b64_tr_b16 v[140:141], v227 offset:34304
	v_add_f32_e32 v118, v124, v146
	v_add_f32_e32 v118, v125, v118
	v_add_f32_e32 v118, v126, v118
	v_add_f32_e32 v118, v127, v118
	v_cvt_pk_bf16_f32 v158, v122, v123
	v_cvt_pk_bf16_f32 v159, v124, v125
	s_waitcnt lgkmcnt(11)
	v_mfma_f32_32x32x16_bf16 v[98:113], v[142:145], v[170:173], v[98:113]
	ds_read_b64_tr_b16 v[120:121], v227 offset:37888
	ds_read_b64_tr_b16 v[122:123], v227 offset:38400
	s_waitcnt lgkmcnt(12)
	v_mfma_f32_32x32x16_bf16 v[66:81], v[178:181], v[170:173], v[66:81]
	v_add_f32_e32 v118, v128, v118
	v_add_f32_e32 v118, v129, v118
	v_add_f32_e32 v118, v82, v118
	v_add_f32_e32 v118, v83, v118
	v_cvt_pk_bf16_f32 v160, v126, v127
	v_cvt_pk_bf16_f32 v161, v128, v129
	ds_read_b64_tr_b16 v[124:125], v227 offset:34816
	ds_read_b64_tr_b16 v[126:127], v227 offset:35328
	v_add_f32_e32 v118, v84, v118
	v_add_f32_e32 v118, v85, v118
	v_add_f32_e32 v118, v86, v118
	v_add_f32_e32 v118, v87, v118
	v_cvt_pk_bf16_f32 v150, v82, v83
	v_cvt_pk_bf16_f32 v151, v84, v85
	s_waitcnt lgkmcnt(13)
	v_mfma_f32_32x32x16_bf16 v[98:113], v[182:185], v[162:165], v[98:113]
	ds_read_b64_tr_b16 v[82:83], v227 offset:38912
	ds_read_b64_tr_b16 v[84:85], v227 offset:39424
	s_waitcnt lgkmcnt(14)
	v_mfma_f32_32x32x16_bf16 v[66:81], v[186:189], v[162:165], v[66:81]
	v_add_f32_e32 v118, v88, v118
	v_add_f32_e32 v118, v89, v118
	v_add_f32_e32 v118, v90, v118
	v_add_f32_e32 v118, v91, v118
	v_cvt_pk_bf16_f32 v152, v86, v87
	v_cvt_pk_bf16_f32 v153, v88, v89
	ds_read_b64_tr_b16 v[86:87], v227 offset:35840
	ds_read_b64_tr_b16 v[88:89], v227 offset:36352
	v_add_f32_e32 v118, v92, v118
	v_add_f32_e32 v118, v93, v118
	v_add_f32_e32 v118, v94, v118
	v_add_f32_e32 v118, v95, v118
	v_cvt_pk_bf16_f32 v146, v90, v91
	v_cvt_pk_bf16_f32 v147, v92, v93
	s_waitcnt lgkmcnt(14)
	v_mfma_f32_32x32x16_bf16 v[98:113], v[134:137], v[154:157], v[98:113]
	ds_read_b64_tr_b16 v[90:91], v227 offset:39936
	ds_read_b64_tr_b16 v[92:93], v227 offset:40448
	v_mfma_f32_32x32x16_bf16 v[66:81], v[130:133], v[154:157], v[66:81]
	v_add_f32_e32 v118, v96, v118
	v_add_f32_e32 v118, v97, v118
	v_add_f32_e32 v118, 0, v118
	v_cvt_pk_bf16_f32 v148, v94, v95
	v_cvt_pk_bf16_f32 v149, v96, v97
	v_lshl_add_u64 v[94:95], v[208:209], 0, s[26:27]
	s_mov_b32 s40, m0
	s_mov_b32 m0, s61
	s_nop 0
	global_load_lds_dwordx4 v[94:95], off
	s_mov_b32 m0, s40
	v_add_f32_e32 v118, v214, v118
	s_waitcnt lgkmcnt(14)
	v_mfma_f32_32x32x16_bf16 v[18:33], v[166:169], v[210:213], v[18:33]
	v_exp_f32_e32 v98, v98
	v_exp_f32_e32 v99, v99
	v_exp_f32_e32 v100, v100
	v_exp_f32_e32 v101, v101
	s_waitcnt lgkmcnt(12)
	v_mfma_f32_32x32x16_bf16 v[34:49], v[166:169], v[114:117], v[34:49]
	v_exp_f32_e32 v102, v102
	v_exp_f32_e32 v103, v103
	v_exp_f32_e32 v104, v104
	v_exp_f32_e32 v105, v105
	ds_read_b128 v[128:131], v228
	ds_read_b128 v[132:135], v228 offset:512
	s_waitcnt lgkmcnt(12)
	v_mfma_f32_32x32x16_bf16 v[18:33], v[158:161], v[138:141], v[18:33]
	v_exp_f32_e32 v106, v106
	v_exp_f32_e32 v107, v107
	v_exp_f32_e32 v108, v108
	v_exp_f32_e32 v109, v109
	ds_read_b128 v[136:139], v228 offset:2048
	ds_read_b128 v[140:143], v228 offset:2560
	s_waitcnt lgkmcnt(12)
	v_mfma_f32_32x32x16_bf16 v[34:49], v[158:161], v[120:123], v[34:49]
	v_exp_f32_e32 v110, v110
	v_exp_f32_e32 v111, v111
	v_exp_f32_e32 v112, v112
	v_exp_f32_e32 v113, v113
	ds_read_b128 v[120:123], v228 offset:4096
	ds_read_b128 v[178:181], v228 offset:4608
	s_waitcnt lgkmcnt(12)
	v_mfma_f32_32x32x16_bf16 v[18:33], v[150:153], v[124:127], v[18:33]
	v_exp_f32_e32 v66, v66
	v_exp_f32_e32 v67, v67
	v_exp_f32_e32 v68, v68
	v_exp_f32_e32 v69, v69
	ds_read_b128 v[124:127], v228 offset:6144
	ds_read_b128 v[114:117], v228 offset:6656
	s_waitcnt lgkmcnt(12)
	v_mfma_f32_32x32x16_bf16 v[34:49], v[150:153], v[82:85], v[34:49]
	v_exp_f32_e32 v70, v70
	v_exp_f32_e32 v71, v71
	v_exp_f32_e32 v72, v72
	v_exp_f32_e32 v73, v73
	s_waitcnt lgkmcnt(10)
	v_mfma_f32_32x32x16_bf16 v[18:33], v[146:149], v[86:89], v[18:33]
	v_exp_f32_e32 v74, v74
	v_exp_f32_e32 v75, v75
	v_exp_f32_e32 v76, v76
	v_exp_f32_e32 v77, v77
	s_waitcnt lgkmcnt(8)
	v_mfma_f32_32x32x16_bf16 v[34:49], v[146:149], v[90:93], v[34:49]
	v_exp_f32_e32 v78, v78
	v_exp_f32_e32 v79, v79
	v_exp_f32_e32 v80, v80
	v_exp_f32_e32 v81, v81
	s_waitcnt vmcnt(0) lgkmcnt(0)
	s_barrier
;   #define RESC() do{ if(!FIXREF&&resc){ asm volatile("s_waitcnt lgkmcnt(0)":::"memory"); \
;       _Pragma("unroll") for(int d_=0;d_<2;++d_) _Pragma("unroll") for(int r=0;r<16;++r)o[d_][r]*=wsf[crow(r,hi)]; } }while(0)
; template<int THRL,bool FIXREF,bool HALFK> __device__ __forceinline__ void attn_unit(float mref,long rowbase,int q0,const bf16*Qh,int PQ,const bf16*__restrict__ Kh_,int PK,const bf16*__restrict__ Vh_,int PV,bf16*Oh,int PO,const bf16*Gh,int PG,u32x4(&okeep)[4],int omode,float lam,float oml,const float ...
;     ...
;   STEP(pB0,pB1,pA0,pA1,NT-1,false,false,false); RESC();
	ds_read_b64_tr_b16 v[182:183], v227 offset:40960
	ds_read_b64_tr_b16 v[184:185], v227 offset:41472
	v_add_f32_e32 v82, v98, v99
	v_add_f32_e32 v82, v100, v82
	v_add_f32_e32 v82, v101, v82
	v_add_f32_e32 v82, v102, v82
	v_add_f32_e32 v119, v103, v82
	v_cvt_pk_bf16_f32 v166, v98, v99
	v_cvt_pk_bf16_f32 v167, v100, v101
	s_waitcnt lgkmcnt(9)
	v_mfma_f32_32x32x16_bf16 v[82:97], v[128:131], v[174:177], v[50:65]
	ds_read_b64_tr_b16 v[98:99], v227 offset:45056
	ds_read_b64_tr_b16 v[100:101], v227 offset:45568
	v_add_f32_e32 v119, v104, v119
	v_add_f32_e32 v119, v105, v119
	v_add_f32_e32 v119, v106, v119
	v_add_f32_e32 v119, v107, v119
	v_cvt_pk_bf16_f32 v168, v102, v103
	v_cvt_pk_bf16_f32 v169, v104, v105
	s_waitcnt lgkmcnt(10)
	v_mfma_f32_32x32x16_bf16 v[50:65], v[132:135], v[174:177], v[50:65]
	ds_read_b64_tr_b16 v[102:103], v227 offset:41984
	ds_read_b64_tr_b16 v[104:105], v227 offset:42496
	v_add_f32_e32 v119, v108, v119
	v_add_f32_e32 v119, v109, v119
	v_add_f32_e32 v119, v110, v119
	v_add_f32_e32 v119, v111, v119
	v_cvt_pk_bf16_f32 v158, v106, v107
	v_cvt_pk_bf16_f32 v159, v108, v109
	s_waitcnt lgkmcnt(11)
	v_mfma_f32_32x32x16_bf16 v[82:97], v[136:139], v[170:173], v[82:97]
	ds_read_b64_tr_b16 v[106:107], v227 offset:46080
	ds_read_b64_tr_b16 v[108:109], v227 offset:46592
	v_add_f32_e32 v119, v112, v119
	v_add_f32_e32 v119, v113, v119
	v_add_f32_e32 v119, v66, v119
	v_add_f32_e32 v119, v67, v119
	v_cvt_pk_bf16_f32 v160, v110, v111
	v_cvt_pk_bf16_f32 v161, v112, v113
	s_waitcnt lgkmcnt(12)
	v_mfma_f32_32x32x16_bf16 v[50:65], v[140:143], v[170:173], v[50:65]
	ds_read_b64_tr_b16 v[110:111], v227 offset:43008
	ds_read_b64_tr_b16 v[112:113], v227 offset:43520
	v_add_f32_e32 v119, v68, v119
	v_add_f32_e32 v119, v69, v119
	v_add_f32_e32 v119, v70, v119
	v_add_f32_e32 v119, v71, v119
	v_cvt_pk_bf16_f32 v150, v66, v67
	v_cvt_pk_bf16_f32 v151, v68, v69
	s_waitcnt lgkmcnt(13)
	v_mfma_f32_32x32x16_bf16 v[82:97], v[120:123], v[162:165], v[82:97]
	ds_read_b64_tr_b16 v[66:67], v227 offset:47104
	ds_read_b64_tr_b16 v[68:69], v227 offset:47616
	v_add_f32_e32 v119, v72, v119
	v_add_f32_e32 v119, v73, v119
	v_add_f32_e32 v119, v74, v119
	v_add_f32_e32 v119, v75, v119
	v_cvt_pk_bf16_f32 v152, v70, v71
	v_cvt_pk_bf16_f32 v153, v72, v73
	s_waitcnt lgkmcnt(14)
	v_mfma_f32_32x32x16_bf16 v[50:65], v[178:181], v[162:165], v[50:65]
	ds_read_b64_tr_b16 v[70:71], v227 offset:44032
	ds_read_b64_tr_b16 v[72:73], v227 offset:44544
	v_add_f32_e32 v119, v76, v119
	v_add_f32_e32 v119, v77, v119
	v_add_f32_e32 v119, v78, v119
	v_add_f32_e32 v119, v79, v119
	v_cvt_pk_bf16_f32 v146, v74, v75
	v_cvt_pk_bf16_f32 v147, v76, v77
	s_waitcnt lgkmcnt(14)
	v_mfma_f32_32x32x16_bf16 v[82:97], v[124:127], v[154:157], v[82:97]
	ds_read_b64_tr_b16 v[74:75], v227 offset:48128
	ds_read_b64_tr_b16 v[76:77], v227 offset:48640
	v_mfma_f32_32x32x16_bf16 v[50:65], v[114:117], v[154:157], v[50:65]
	v_add_f32_e32 v114, v80, v119
	v_add_f32_e32 v114, v81, v114
	v_add_f32_e32 v114, 0, v114
	v_cvt_pk_bf16_f32 v148, v78, v79
	v_cvt_pk_bf16_f32 v149, v80, v81
	s_waitcnt lgkmcnt(14)
	v_mfma_f32_32x32x16_bf16 v[18:33], v[166:169], v[182:185], v[18:33]
	s_nop 1
	v_exp_f32_e32 v82, v82
	v_exp_f32_e32 v83, v83
	v_exp_f32_e32 v84, v84
	v_exp_f32_e32 v85, v85
	s_waitcnt lgkmcnt(12)
	v_mfma_f32_32x32x16_bf16 v[34:49], v[166:169], v[98:101], v[34:49]
	v_exp_f32_e32 v86, v86
	v_exp_f32_e32 v87, v87
	v_exp_f32_e32 v88, v88
	v_exp_f32_e32 v89, v89
	s_waitcnt lgkmcnt(10)
	v_mfma_f32_32x32x16_bf16 v[18:33], v[158:161], v[102:105], v[18:33]
	v_exp_f32_e32 v90, v90
	v_exp_f32_e32 v91, v91
	v_exp_f32_e32 v92, v92
	v_exp_f32_e32 v93, v93
	s_waitcnt lgkmcnt(8)
	v_mfma_f32_32x32x16_bf16 v[34:49], v[158:161], v[106:109], v[34:49]
	v_exp_f32_e32 v94, v94
	v_exp_f32_e32 v95, v95
	v_exp_f32_e32 v96, v96
	v_exp_f32_e32 v97, v97
	s_waitcnt lgkmcnt(6)
; #define SBAR() __builtin_amdgcn_sched_barrier(0)
;   #define PKW(P,B) cvtpk_s(P[B],P[B+1])
; __device__ __forceinline__ void pv(f32x16*o,int vb,bf16x8 pa0,bf16x8 pa1,bf16x8 pa2,bf16x8 pa3){
;   #pragma unroll
;   for(int d0=0;d0<2;++d0){s16x4 lo[4],hi[4];
;     #pragma unroll
;     for(int ks=0;ks<4;++ks){
;       asm volatile("ds_read_b64_tr_b16 %0,%1 offset:%c2":"=&v"(lo[ks]):"v"(vb),"i"(d0*4096+ks*1024):"memory");
;       asm volatile("ds_read_b64_tr_b16 %0,%1 offset:%c2":"=&v"(hi[ks]):"v"(vb),"i"(d0*4096+ks*1024+512):"memory");}
;     asm volatile("s_waitcnt lgkmcnt(0)":::"memory");SBAR();
;     ...
;     o[d0]=__builtin_amdgcn_mfma_f32_32x32x16_bf16(pa0,PK(0),o[d0],0,0,0);
;     o[d0]=__builtin_amdgcn_mfma_f32_32x32x16_bf16(pa1,PK(1),o[d0],0,0,0);
;     o[d0]=__builtin_amdgcn_mfma_f32_32x32x16_bf16(pa2,PK(2),o[d0],0,0,0);
;     o[d0]=__builtin_amdgcn_mfma_f32_32x32x16_bf16(pa3,PK(3),o[d0],0,0,0);
;     ...
;   }
; }
; template<int THRL,bool FIXREF,bool HALFK> __device__ __forceinline__ void attn_unit(float mref,long rowbase,int q0,const bf16*Qh,int PQ,const bf16*__restrict__ Kh_,int PK,const bf16*__restrict__ Vh_,int PV,bf16*Oh,int PO,const bf16*Gh,int PG,u32x4(&okeep)[4],int omode,float lam,float oml,const float ...
;     ...
;   int t=1;
;     ...
;   for(;t+5<NT;t+=2){
;     STEP(pB0,pB1,pA0,pA1,t,true,true,true);     WAIT_BAR(2); RESC(); ROT();
;     STEP(pA0,pA1,pB0,pB1,t+1,true,true,true);   WAIT_BAR(2); RESC(); ROT();
;   }
;     ...
;   for(;t+1<NT;t+=2){
;     STEP(pB0,pB1,pA0,pA1,t,(t+3<NT),(t+1<NT),(t+1<NT));       ENDW(t);   RESC(); ROT();
;     STEP(pA0,pA1,pB0,pB1,t+1,(t+4<NT),(t+2<NT),(t+2<NT));     ENDW(t+1); RESC(); ROT();
;   }
;   STEP(pB0,pB1,pA0,pA1,NT-1,false,false,false); RESC();
;   { float sacc=pB0[0]+pB0[1]; _Pragma("unroll") for(int r=2;r<16;++r)sacc+=pB0[r]; _Pragma("unroll") for(int r=0;r<16;++r)sacc+=pB1[r]; l_reg+=sacc;
;     pw0=(u32x4){PKW(pB0,0),PKW(pB0,2),PKW(pB0,4),PKW(pB0,6)};pw1=(u32x4){PKW(pB0,8),PKW(pB0,10),PKW(pB0,12),PKW(pB0,14)};pw2=(u32x4){PKW(pB1,0),PKW(pB1,2),PKW(pB1,4),PKW(pB1,6)};pw3=(u32x4){PKW(pB1,8),PKW(pB1,10),PKW(pB1,12),PKW(pB1,14)};
;     SBAR(); pv(o,vb0+sl_cur,PAF(0),PAF(1),PAF(2),PAF(3)); }
;     ...
;   {auto rr=__builtin_amdgcn_permlane32_swap(__float_as_uint(l_reg),__float_as_uint(l_reg),false,false);l_reg=__uint_as_float(rr[0])+__uint_as_float(rr[1]);}
;   if(hi==0)wsf[32+r32]=l_reg;asm volatile("s_waitcnt lgkmcnt(0)":::"memory");
	v_mfma_f32_32x32x16_bf16 v[18:33], v[150:153], v[110:113], v[18:33]
	v_exp_f32_e32 v50, v50
	v_exp_f32_e32 v51, v51
	v_exp_f32_e32 v52, v52
	v_exp_f32_e32 v53, v53
	s_waitcnt lgkmcnt(4)
	v_mfma_f32_32x32x16_bf16 v[34:49], v[150:153], v[66:69], v[34:49]
	v_exp_f32_e32 v54, v54
	v_exp_f32_e32 v55, v55
	v_exp_f32_e32 v56, v56
	v_exp_f32_e32 v57, v57
	s_waitcnt lgkmcnt(2)
	v_mfma_f32_32x32x16_bf16 v[18:33], v[146:149], v[70:73], v[18:33]
	v_exp_f32_e32 v58, v58
	v_exp_f32_e32 v59, v59
	v_exp_f32_e32 v60, v60
	v_exp_f32_e32 v61, v61
	s_waitcnt lgkmcnt(0)
	v_mfma_f32_32x32x16_bf16 v[34:49], v[146:149], v[74:77], v[34:49]
	v_exp_f32_e32 v62, v62
	v_exp_f32_e32 v63, v63
	v_exp_f32_e32 v64, v64
	v_exp_f32_e32 v65, v65
	v_add_f32_e32 v66, v82, v83
	v_add_f32_e32 v66, v84, v66
	v_add_f32_e32 v66, v85, v66
	v_add_f32_e32 v66, v86, v66
	v_add_f32_e32 v66, v87, v66
	v_add_f32_e32 v66, v88, v66
	v_add_f32_e32 v66, v89, v66
	v_add_f32_e32 v66, v90, v66
	v_add_f32_e32 v66, v91, v66
	v_add_f32_e32 v66, v92, v66
	v_add_f32_e32 v66, v93, v66
	v_add_f32_e32 v66, v94, v66
	v_add_f32_e32 v66, v95, v66
	v_add_f32_e32 v66, v96, v66
	v_add_f32_e32 v66, v97, v66
	v_add_f32_e32 v66, v50, v66
	v_add_f32_e32 v66, v51, v66
	v_add_f32_e32 v66, v52, v66
	v_add_f32_e32 v66, v53, v66
	v_add_f32_e32 v66, v54, v66
	v_add_f32_e32 v66, v55, v66
	v_add_f32_e32 v66, v56, v66
	v_add_f32_e32 v66, v57, v66
	v_add_f32_e32 v66, v58, v66
	v_add_f32_e32 v66, v59, v66
	v_add_f32_e32 v66, v60, v66
	v_add_f32_e32 v66, v61, v66
	v_add_f32_e32 v66, v62, v66
	v_add_f32_e32 v66, v63, v66
	v_add_f32_e32 v66, v64, v66
	v_add_f32_e32 v66, v65, v66
	v_add_f32_e32 v67, v118, v114
	v_add_f32_e32 v66, v67, v66
	v_cvt_pk_bf16_f32 v68, v82, v83
	v_cvt_pk_bf16_f32 v69, v84, v85
	v_cvt_pk_bf16_f32 v70, v86, v87
	v_cvt_pk_bf16_f32 v71, v88, v89
	v_cvt_pk_bf16_f32 v72, v90, v91
	v_cvt_pk_bf16_f32 v73, v92, v93
	v_cvt_pk_bf16_f32 v74, v94, v95
	v_cvt_pk_bf16_f32 v75, v96, v97
	v_cvt_pk_bf16_f32 v50, v50, v51
	v_cvt_pk_bf16_f32 v51, v52, v53
	v_cvt_pk_bf16_f32 v52, v54, v55
	v_cvt_pk_bf16_f32 v53, v56, v57
	v_cvt_pk_bf16_f32 v54, v58, v59
	v_cvt_pk_bf16_f32 v55, v60, v61
	v_cvt_pk_bf16_f32 v56, v62, v63
	v_cvt_pk_bf16_f32 v57, v64, v65
	ds_read_b64_tr_b16 v[58:59],v0 offset:0
	ds_read_b64_tr_b16 v[60:61],v0 offset:512
	ds_read_b64_tr_b16 v[62:63],v0 offset:1024
	ds_read_b64_tr_b16 v[64:65],v0 offset:1536
	ds_read_b64_tr_b16 v[76:77],v0 offset:2048
	ds_read_b64_tr_b16 v[78:79],v0 offset:2560
	ds_read_b64_tr_b16 v[80:81],v0 offset:3072
	ds_read_b64_tr_b16 v[82:83],v0 offset:3584
	s_waitcnt lgkmcnt(0)
	s_nop 0
	v_mfma_f32_32x32x16_bf16 v[18:33], v[68:71], v[58:61], v[18:33]
	ds_read_b64_tr_b16 v[58:59],v0 offset:4096
	ds_read_b64_tr_b16 v[60:61],v0 offset:4608
	v_mfma_f32_32x32x16_bf16 v[18:33], v[72:75], v[62:65], v[18:33]
	ds_read_b64_tr_b16 v[62:63],v0 offset:5120
	ds_read_b64_tr_b16 v[64:65],v0 offset:5632
	v_mfma_f32_32x32x16_bf16 v[18:33], v[50:53], v[76:79], v[18:33]
	ds_read_b64_tr_b16 v[76:77],v0 offset:6144
	ds_read_b64_tr_b16 v[78:79],v0 offset:6656
	v_mfma_f32_32x32x16_bf16 v[18:33], v[54:57], v[80:83], v[18:33]
	ds_read_b64_tr_b16 v[80:81],v0 offset:7168
	ds_read_b64_tr_b16 v[82:83],v0 offset:7680
	s_waitcnt lgkmcnt(0)
	v_mfma_f32_32x32x16_bf16 v[34:49], v[68:71], v[58:61], v[34:49]
	v_mov_b32_e32 v0, v66
	s_nop 1
	v_permlane32_swap_b32_e32 v66, v0
	v_cmp_gt_u32_e32 vcc, 32, v205
	v_mfma_f32_32x32x16_bf16 v[34:49], v[72:75], v[62:65], v[34:49]
	v_mfma_f32_32x32x16_bf16 v[34:49], v[50:53], v[76:79], v[34:49]
	v_mfma_f32_32x32x16_bf16 v[34:49], v[54:57], v[80:83], v[34:49]
	s_and_saveexec_b64 s[40:41], vcc
	s_cbranch_execz .LBB0_449
	v_lshl_add_u32 v50, v216, 2, s42
	v_add_f32_e32 v0, v66, v0
	ds_write_b32 v50, v0 offset:49280
	s_branch .LBB0_449

; #define WAIT_BAR(N) asm volatile("s_waitcnt vmcnt(" #N ") lgkmcnt(0)\n\ts_barrier":::"memory")
;   #define RESC() do{ if(!FIXREF&&resc){ asm volatile("s_waitcnt lgkmcnt(0)":::"memory"); \
;       _Pragma("unroll") for(int d_=0;d_<2;++d_) _Pragma("unroll") for(int r=0;r<16;++r)o[d_][r]*=wsf[crow(r,hi)]; } }while(0)
;   #define ROT() do{sl_prev=sl_cur;sl_cur=sl_next;sl_next=(sl_next==(NSLOT-1)*SLOTB)?0:sl_next+SLOTB;}while(0)
; template<int THRL,bool FIXREF,bool HALFK> __device__ __forceinline__ void attn_unit(float mref,long rowbase,int q0,const bf16*Qh,int PQ,const bf16*__restrict__ Kh_,int PK,const bf16*__restrict__ Vh_,int PV,bf16*Oh,int PO,const bf16*Gh,int PG,u32x4(&okeep)[4],int omode,float lam,float oml,const float ...
;     ...
;   int t=1;
;     ...
;   for(;t+5<NT;t+=2){
;     STEP(pB0,pB1,pA0,pA1,t,true,true,true);     WAIT_BAR(2); RESC(); ROT();
.LBB0_461:
	v_add_u32_e32 v0, s87, v213
	ds_read_b64_tr_b16 v[228:229], v0 offset:24576
	ds_read_b64_tr_b16 v[230:231], v0 offset:25088
	v_add_f32_e32 v102, v82, v83
	v_add_f32_e32 v102, v84, v102
	v_add_f32_e32 v102, v85, v102
	v_add_f32_e32 v102, v86, v102
	v_add_f32_e32 v102, v87, v102
	v_cvt_pk_bf16_f32 v158, v82, v83
	v_cvt_pk_bf16_f32 v159, v84, v85
	s_waitcnt lgkmcnt(5)
	v_mfma_f32_32x32x16_bf16 v[114:129], v[98:101], v[166:169], v[50:65]
	ds_read_b64_tr_b16 v[82:83], v0 offset:28672
	ds_read_b64_tr_b16 v[84:85], v0 offset:29184
	v_add_f32_e32 v98, v88, v102
	v_add_f32_e32 v98, v89, v98
	v_add_f32_e32 v98, v90, v98
	v_add_f32_e32 v146, v91, v98
	s_waitcnt lgkmcnt(6)
	v_mfma_f32_32x32x16_bf16 v[98:113], v[134:137], v[166:169], v[50:65]
	v_cvt_pk_bf16_f32 v160, v86, v87
	v_cvt_pk_bf16_f32 v161, v88, v89
	ds_read_b64_tr_b16 v[86:87], v0 offset:25600
	ds_read_b64_tr_b16 v[88:89], v0 offset:26112
	v_add_f32_e32 v134, v92, v146
	v_add_f32_e32 v134, v93, v134
	v_add_f32_e32 v134, v94, v134
	v_add_f32_e32 v134, v95, v134
	v_cvt_pk_bf16_f32 v154, v90, v91
	v_cvt_pk_bf16_f32 v155, v92, v93
	s_waitcnt lgkmcnt(7)
	v_mfma_f32_32x32x16_bf16 v[114:129], v[138:141], v[162:165], v[114:129]
	ds_read_b64_tr_b16 v[90:91], v0 offset:29696
	ds_read_b64_tr_b16 v[92:93], v0 offset:30208
	s_waitcnt lgkmcnt(8)
	v_mfma_f32_32x32x16_bf16 v[98:113], v[130:133], v[162:165], v[98:113]
	v_add_f32_e32 v130, v96, v134
	v_add_f32_e32 v130, v97, v130
	v_add_f32_e32 v130, v66, v130
	v_add_f32_e32 v130, v67, v130
	v_cvt_pk_bf16_f32 v156, v94, v95
	v_cvt_pk_bf16_f32 v157, v96, v97
	ds_read_b64_tr_b16 v[94:95], v0 offset:26624
	ds_read_b64_tr_b16 v[96:97], v0 offset:27136
	v_add_f32_e32 v130, v68, v130
	v_add_f32_e32 v130, v69, v130
	v_add_f32_e32 v130, v70, v130
	v_add_f32_e32 v130, v71, v130
	v_cvt_pk_bf16_f32 v150, v66, v67
	v_cvt_pk_bf16_f32 v151, v68, v69
	ds_read_b64_tr_b16 v[66:67], v0 offset:30720
	ds_read_b64_tr_b16 v[68:69], v0 offset:31232
	v_add_f32_e32 v130, v72, v130
	v_add_f32_e32 v130, v73, v130
	v_add_f32_e32 v130, v74, v130
	v_add_f32_e32 v130, v75, v130
	v_cvt_pk_bf16_f32 v152, v70, v71
	v_cvt_pk_bf16_f32 v153, v72, v73
	ds_read_b64_tr_b16 v[70:71], v0 offset:27648
	ds_read_b64_tr_b16 v[72:73], v0 offset:28160
	v_add_f32_e32 v130, v76, v130
	v_add_f32_e32 v130, v77, v130
	v_add_f32_e32 v130, v78, v130
	v_add_f32_e32 v130, v79, v130
	v_cvt_pk_bf16_f32 v146, v74, v75
	v_cvt_pk_bf16_f32 v147, v76, v77
	ds_read_b64_tr_b16 v[74:75], v0 offset:31744
	ds_read_b64_tr_b16 v[76:77], v0 offset:32256
	v_add_f32_e32 v0, v80, v130
	v_add_f32_e32 v0, v81, v0
	v_add_f32_e32 v0, 0, v0
	v_cvt_pk_bf16_f32 v148, v78, v79
	v_cvt_pk_bf16_f32 v149, v80, v81
	v_add_f32_e32 v0, v227, v0
	s_waitcnt lgkmcnt(14)
	v_mfma_f32_32x32x16_bf16 v[18:33], v[158:161], v[228:231], v[18:33]
	v_exp_f32_e32 v114, v114
	v_exp_f32_e32 v115, v115
	v_exp_f32_e32 v116, v116
	v_exp_f32_e32 v117, v117
	v_lshl_add_u64 v[78:79], v[144:145], 0, s[36:37]
	s_add_i32 s20, s86, s81
	s_mov_b32 m0, s20
	s_nop 0
	global_load_lds_dwordx4 v[78:79], off
	s_waitcnt lgkmcnt(12)
	v_mfma_f32_32x32x16_bf16 v[34:49], v[158:161], v[82:85], v[34:49]
	v_exp_f32_e32 v118, v118
	v_exp_f32_e32 v119, v119
	v_exp_f32_e32 v120, v120
	v_exp_f32_e32 v121, v121
	v_lshl_add_u64 v[78:79], v[142:143], 0, s[22:23]
	s_add_i32 s20, s85, s80
	s_mov_b32 m0, s20
	s_nop 0
	global_load_lds_dwordx4 v[78:79], off
	v_add_u32_e32 v82, s85, v214
	ds_read_b128 v[78:81], v82
	ds_read_b128 v[130:133], v82 offset:512
	s_waitcnt lgkmcnt(12)
	v_mfma_f32_32x32x16_bf16 v[18:33], v[154:157], v[86:89], v[18:33]
	v_exp_f32_e32 v122, v122
	v_exp_f32_e32 v123, v123
	v_exp_f32_e32 v124, v124
	v_exp_f32_e32 v125, v125
	ds_read_b128 v[134:137], v82 offset:2048
	ds_read_b128 v[138:141], v82 offset:2560
	s_waitcnt lgkmcnt(12)
	v_mfma_f32_32x32x16_bf16 v[34:49], v[154:157], v[90:93], v[34:49]
	v_exp_f32_e32 v126, v126
	v_exp_f32_e32 v127, v127
	v_exp_f32_e32 v128, v128
	v_exp_f32_e32 v129, v129
	s_waitcnt lgkmcnt(10)
	v_mfma_f32_32x32x16_bf16 v[18:33], v[150:153], v[94:97], v[18:33]
	v_exp_f32_e32 v98, v98
	v_exp_f32_e32 v99, v99
	v_exp_f32_e32 v100, v100
	v_exp_f32_e32 v101, v101
	s_waitcnt lgkmcnt(8)
	v_mfma_f32_32x32x16_bf16 v[34:49], v[150:153], v[66:69], v[34:49]
	v_exp_f32_e32 v102, v102
	v_exp_f32_e32 v103, v103
	v_exp_f32_e32 v104, v104
	v_exp_f32_e32 v105, v105
	s_waitcnt lgkmcnt(6)
	v_mfma_f32_32x32x16_bf16 v[18:33], v[146:149], v[70:73], v[18:33]
	v_exp_f32_e32 v106, v106
	v_exp_f32_e32 v107, v107
	v_exp_f32_e32 v108, v108
	v_exp_f32_e32 v109, v109
	s_waitcnt lgkmcnt(4)
	v_mfma_f32_32x32x16_bf16 v[34:49], v[146:149], v[74:77], v[34:49]
	v_exp_f32_e32 v110, v110
	v_exp_f32_e32 v111, v111
	v_exp_f32_e32 v112, v112
	v_exp_f32_e32 v113, v113
	s_waitcnt vmcnt(2) lgkmcnt(0)
	s_barrier
; #define WAIT_BAR(N) asm volatile("s_waitcnt vmcnt(" #N ") lgkmcnt(0)\n\ts_barrier":::"memory")
;   #define RESC() do{ if(!FIXREF&&resc){ asm volatile("s_waitcnt lgkmcnt(0)":::"memory"); \
;       _Pragma("unroll") for(int d_=0;d_<2;++d_) _Pragma("unroll") for(int r=0;r<16;++r)o[d_][r]*=wsf[crow(r,hi)]; } }while(0)
;   #define ROT() do{sl_prev=sl_cur;sl_cur=sl_next;sl_next=(sl_next==(NSLOT-1)*SLOTB)?0:sl_next+SLOTB;}while(0)
; template<int THRL,bool FIXREF,bool HALFK> __device__ __forceinline__ void attn_unit(float mref,long rowbase,int q0,const bf16*Qh,int PQ,const bf16*__restrict__ Kh_,int PK,const bf16*__restrict__ Vh_,int PV,bf16*Oh,int PO,const bf16*Gh,int PG,u32x4(&okeep)[4],int omode,float lam,float oml,const float ...
;     ...
;   int t=1;
;     ...
;   for(;t+5<NT;t+=2){
;     STEP(pB0,pB1,pA0,pA1,t,true,true,true);     WAIT_BAR(2); RESC(); ROT();
;     STEP(pA0,pA1,pB0,pB1,t+1,true,true,true);   WAIT_BAR(2); RESC(); ROT();
	s_add_i32 s20, s85, 0x2000
	s_cmpk_lg_i32 s85, 0x4000
	s_cselect_b32 s20, s20, 0
	v_add_u32_e32 v227, s86, v213
	ds_read_b64_tr_b16 v[228:229], v227 offset:24576
	ds_read_b64_tr_b16 v[230:231], v227 offset:25088
	s_waitcnt lgkmcnt(5)
	v_mfma_f32_32x32x16_bf16 v[82:97], v[78:81], v[166:169], v[50:65]
	v_add_f32_e32 v66, v114, v115
	v_add_f32_e32 v66, v116, v66
	v_add_f32_e32 v66, v117, v66
	v_add_f32_e32 v66, v118, v66
	v_add_f32_e32 v66, v119, v66
	v_cvt_pk_bf16_f32 v158, v114, v115
	v_cvt_pk_bf16_f32 v159, v116, v117
	ds_read_b64_tr_b16 v[114:115], v227 offset:28672
	ds_read_b64_tr_b16 v[116:117], v227 offset:29184
	v_add_f32_e32 v66, v120, v66
	v_add_f32_e32 v66, v121, v66
	v_add_f32_e32 v66, v122, v66
	v_add_f32_e32 v146, v123, v66
	s_waitcnt lgkmcnt(6)
	v_mfma_f32_32x32x16_bf16 v[66:81], v[130:133], v[166:169], v[50:65]
	v_cvt_pk_bf16_f32 v160, v118, v119
	v_cvt_pk_bf16_f32 v161, v120, v121
	ds_read_b64_tr_b16 v[118:119], v227 offset:25600
	ds_read_b64_tr_b16 v[120:121], v227 offset:26112
	s_waitcnt lgkmcnt(7)
	v_mfma_f32_32x32x16_bf16 v[82:97], v[134:137], v[162:165], v[82:97]
	v_add_f32_e32 v130, v124, v146
	v_add_f32_e32 v130, v125, v130
	v_add_f32_e32 v130, v126, v130
	v_add_f32_e32 v130, v127, v130
	v_cvt_pk_bf16_f32 v154, v122, v123
	v_cvt_pk_bf16_f32 v155, v124, v125
	ds_read_b64_tr_b16 v[122:123], v227 offset:29696
	ds_read_b64_tr_b16 v[124:125], v227 offset:30208
	s_waitcnt lgkmcnt(8)
	v_mfma_f32_32x32x16_bf16 v[66:81], v[138:141], v[162:165], v[66:81]
	v_add_f32_e32 v130, v128, v130
	v_add_f32_e32 v130, v129, v130
	v_add_f32_e32 v130, v98, v130
	v_add_f32_e32 v130, v99, v130
	v_cvt_pk_bf16_f32 v156, v126, v127
	v_cvt_pk_bf16_f32 v157, v128, v129
	ds_read_b64_tr_b16 v[126:127], v227 offset:26624
	ds_read_b64_tr_b16 v[128:129], v227 offset:27136
	v_add_f32_e32 v130, v100, v130
	v_add_f32_e32 v130, v101, v130
	v_add_f32_e32 v130, v102, v130
	v_add_f32_e32 v130, v103, v130
	v_cvt_pk_bf16_f32 v150, v98, v99
	v_cvt_pk_bf16_f32 v151, v100, v101
	ds_read_b64_tr_b16 v[232:233], v227 offset:30720
	ds_read_b64_tr_b16 v[234:235], v227 offset:31232
	v_add_f32_e32 v98, v104, v130
	v_add_f32_e32 v98, v105, v98
	v_add_f32_e32 v98, v106, v98
	v_add_f32_e32 v98, v107, v98
	v_cvt_pk_bf16_f32 v152, v102, v103
	v_cvt_pk_bf16_f32 v153, v104, v105
	ds_read_b64_tr_b16 v[102:103], v227 offset:27648
	ds_read_b64_tr_b16 v[104:105], v227 offset:28160
	v_add_f32_e32 v98, v108, v98
	v_add_f32_e32 v98, v109, v98
	v_add_f32_e32 v98, v110, v98
	v_add_f32_e32 v98, v111, v98
	v_cvt_pk_bf16_f32 v146, v106, v107
	v_cvt_pk_bf16_f32 v147, v108, v109
	ds_read_b64_tr_b16 v[106:107], v227 offset:31744
	ds_read_b64_tr_b16 v[108:109], v227 offset:32256
	v_add_f32_e32 v98, v112, v98
	v_add_f32_e32 v98, v113, v98
	v_add_f32_e32 v98, 0, v98
	v_cvt_pk_bf16_f32 v148, v110, v111
	v_cvt_pk_bf16_f32 v149, v112, v113
	s_nop 0
	v_add_f32_e32 v227, v0, v98
	s_waitcnt lgkmcnt(14)
	v_mfma_f32_32x32x16_bf16 v[18:33], v[158:161], v[228:231], v[18:33]
	v_exp_f32_e32 v82, v82
	v_exp_f32_e32 v83, v83
	v_exp_f32_e32 v84, v84
	v_exp_f32_e32 v85, v85
	v_lshl_add_u64 v[98:99], v[144:145], 0, s[96:97]
	s_add_i32 s48, s85, s81
	s_mov_b32 m0, s48
	s_nop 0
	global_load_lds_dwordx4 v[98:99], off
	s_waitcnt lgkmcnt(12)
	v_mfma_f32_32x32x16_bf16 v[34:49], v[158:161], v[114:117], v[34:49]
	v_exp_f32_e32 v86, v86
	v_exp_f32_e32 v87, v87
	v_exp_f32_e32 v88, v88
	v_exp_f32_e32 v89, v89
	v_lshl_add_u64 v[142:143], v[142:143], 0, s[4:5]
	s_add_i32 s48, s20, s80
	s_mov_b32 m0, s48
	s_nop 0
	global_load_lds_dwordx4 v[142:143], off
	v_add_u32_e32 v0, s20, v214
	ds_read_b128 v[98:101], v0
	ds_read_b128 v[134:137], v0 offset:512
	s_waitcnt lgkmcnt(12)
	v_mfma_f32_32x32x16_bf16 v[18:33], v[154:157], v[118:121], v[18:33]
	v_exp_f32_e32 v90, v90
	v_exp_f32_e32 v91, v91
	v_exp_f32_e32 v92, v92
	v_exp_f32_e32 v93, v93
	ds_read_b128 v[138:141], v0 offset:2048
	ds_read_b128 v[130:133], v0 offset:2560
	s_waitcnt lgkmcnt(12)
	v_mfma_f32_32x32x16_bf16 v[34:49], v[154:157], v[122:125], v[34:49]
	v_exp_f32_e32 v94, v94
	v_exp_f32_e32 v95, v95
	v_exp_f32_e32 v96, v96
	v_exp_f32_e32 v97, v97
	s_waitcnt lgkmcnt(10)
	v_mfma_f32_32x32x16_bf16 v[18:33], v[150:153], v[126:129], v[18:33]
	v_exp_f32_e32 v66, v66
	v_exp_f32_e32 v67, v67
	v_exp_f32_e32 v68, v68
	v_exp_f32_e32 v69, v69
	s_waitcnt lgkmcnt(8)
	v_mfma_f32_32x32x16_bf16 v[34:49], v[150:153], v[232:235], v[34:49]
	v_exp_f32_e32 v70, v70
	v_exp_f32_e32 v71, v71
	v_exp_f32_e32 v72, v72
	v_exp_f32_e32 v73, v73
	s_waitcnt lgkmcnt(6)
	v_mfma_f32_32x32x16_bf16 v[18:33], v[146:149], v[102:105], v[18:33]
	v_exp_f32_e32 v74, v74
	v_exp_f32_e32 v75, v75
	v_exp_f32_e32 v76, v76
	v_exp_f32_e32 v77, v77
	s_waitcnt lgkmcnt(4)
	v_mfma_f32_32x32x16_bf16 v[34:49], v[146:149], v[106:109], v[34:49]
	v_exp_f32_e32 v78, v78
	v_exp_f32_e32 v79, v79
	v_exp_f32_e32 v80, v80
	v_exp_f32_e32 v81, v81
	s_add_i32 s48, s20, 0x2000
	s_waitcnt vmcnt(2) lgkmcnt(0)
	s_barrier
	s_cmpk_lg_i32 s20, 0x4000
	s_mov_b32 s87, s85
	s_cselect_b32 s85, s48, 0
	s_add_i32 s84, s84, 2
	v_lshl_add_u64 v[144:145], v[144:145], 0, s[92:93]
	s_mov_b32 s86, s20
	s_cmp_gt_u32 s84, 56
	s_cbranch_scc0 .LBB0_461
;   #define RESC() do{ if(!FIXREF&&resc){ asm volatile("s_waitcnt lgkmcnt(0)":::"memory"); \
;       _Pragma("unroll") for(int d_=0;d_<2;++d_) _Pragma("unroll") for(int r=0;r<16;++r)o[d_][r]*=wsf[crow(r,hi)]; } }while(0)
;   #define ROT() do{sl_prev=sl_cur;sl_cur=sl_next;sl_next=(sl_next==(NSLOT-1)*SLOTB)?0:sl_next+SLOTB;}while(0)
;   #define ENDW(tt) do{ if((tt)+3<NT){WAIT_BAR(2);} else if((tt)+2<NT){WAIT_BAR(1);} else {WAIT_BAR(0);} }while(0)
; template<int THRL,bool FIXREF,bool HALFK> __device__ __forceinline__ void attn_unit(float mref,long rowbase,int q0,const bf16*Qh,int PQ,const bf16*__restrict__ Kh_,int PK,const bf16*__restrict__ Vh_,int PV,bf16*Oh,int PO,const bf16*Gh,int PG,u32x4(&okeep)[4],int omode,float lam,float oml,const float ...
;     ...
;   for(;t+1<NT;t+=2){
;     STEP(pB0,pB1,pA0,pA1,t,(t+3<NT),(t+1<NT),(t+1<NT));       ENDW(t);   RESC(); ROT();
	s_and_b32 s20, s83, 0x3fffffc0
	s_lshl_b32 s20, s20, 2
	s_add_i32 s20, s20, 0
	s_cmp_lg_u32 0, -1
	s_cselect_b32 s50, 0, 0
	s_add_i32 s48, s50, 0x6000
	v_add_u32_e32 v0, s48, v216
	v_add3_u32 v0, v0, v215, v217
	ds_read_b64_tr_b16 v[142:143], v213 offset:32768
	ds_read_b64_tr_b16 v[144:145], v213 offset:33280
	v_add_f32_e32 v102, v82, v83
	v_add_f32_e32 v102, v84, v102
	v_add_f32_e32 v102, v85, v102
	v_add_f32_e32 v102, v86, v102
	v_add_f32_e32 v102, v87, v102
	v_cvt_pk_bf16_f32 v158, v82, v83
	v_cvt_pk_bf16_f32 v159, v84, v85
	s_waitcnt lgkmcnt(5)
	v_mfma_f32_32x32x16_bf16 v[114:129], v[98:101], v[166:169], v[50:65]
	ds_read_b64_tr_b16 v[82:83], v213 offset:36864
	ds_read_b64_tr_b16 v[84:85], v213 offset:37376
	v_add_f32_e32 v98, v88, v102
	v_add_f32_e32 v98, v89, v98
	v_add_f32_e32 v98, v90, v98
	v_add_f32_e32 v146, v91, v98
	v_cvt_pk_bf16_f32 v160, v86, v87
	v_cvt_pk_bf16_f32 v161, v88, v89
	s_waitcnt lgkmcnt(6)
	v_mfma_f32_32x32x16_bf16 v[98:113], v[134:137], v[166:169], v[50:65]
	ds_read_b64_tr_b16 v[86:87], v213 offset:33792
	ds_read_b64_tr_b16 v[88:89], v213 offset:34304
	v_add_f32_e32 v134, v92, v146
	v_add_f32_e32 v134, v93, v134
	v_add_f32_e32 v134, v94, v134
	v_add_f32_e32 v134, v95, v134
	v_cvt_pk_bf16_f32 v154, v90, v91
	v_cvt_pk_bf16_f32 v155, v92, v93
	s_waitcnt lgkmcnt(7)
	v_mfma_f32_32x32x16_bf16 v[114:129], v[138:141], v[162:165], v[114:129]
	ds_read_b64_tr_b16 v[90:91], v213 offset:37888
	ds_read_b64_tr_b16 v[92:93], v213 offset:38400
	s_waitcnt lgkmcnt(8)
	v_mfma_f32_32x32x16_bf16 v[98:113], v[130:133], v[162:165], v[98:113]
	v_add_f32_e32 v130, v96, v134
	v_add_f32_e32 v130, v97, v130
	v_add_f32_e32 v130, v66, v130
	v_add_f32_e32 v130, v67, v130
	v_cvt_pk_bf16_f32 v156, v94, v95
	v_cvt_pk_bf16_f32 v157, v96, v97
	ds_read_b64_tr_b16 v[94:95], v213 offset:34816
	ds_read_b64_tr_b16 v[96:97], v213 offset:35328
	v_add_f32_e32 v130, v68, v130
	v_add_f32_e32 v130, v69, v130
	v_add_f32_e32 v130, v70, v130
	v_add_f32_e32 v130, v71, v130
	v_cvt_pk_bf16_f32 v150, v66, v67
	v_cvt_pk_bf16_f32 v151, v68, v69
	ds_read_b64_tr_b16 v[66:67], v213 offset:38912
	ds_read_b64_tr_b16 v[68:69], v213 offset:39424
	v_add_f32_e32 v130, v72, v130
	v_add_f32_e32 v130, v73, v130
	v_add_f32_e32 v130, v74, v130
	v_add_f32_e32 v130, v75, v130
	v_cvt_pk_bf16_f32 v152, v70, v71
	v_cvt_pk_bf16_f32 v153, v72, v73
	ds_read_b64_tr_b16 v[70:71], v213 offset:35840
	ds_read_b64_tr_b16 v[72:73], v213 offset:36352
	v_add_f32_e32 v130, v76, v130
	v_add_f32_e32 v130, v77, v130
	v_add_f32_e32 v130, v78, v130
	v_add_f32_e32 v130, v79, v130
	v_cvt_pk_bf16_f32 v146, v74, v75
	v_cvt_pk_bf16_f32 v147, v76, v77
	ds_read_b64_tr_b16 v[74:75], v213 offset:39936
	ds_read_b64_tr_b16 v[76:77], v213 offset:40448
	v_add_f32_e32 v130, v80, v130
	v_add_f32_e32 v130, v81, v130
	v_add_f32_e32 v130, 0, v130
	v_cvt_pk_bf16_f32 v148, v78, v79
	v_cvt_pk_bf16_f32 v149, v80, v81
	s_mov_b64 s[48:49], 0x1f0000
	v_lshl_add_u64 v[78:79], v[174:175], 0, s[48:49]
	s_add_i32 s48, s50, s82
	s_add_i32 s49, s48, 0x4000
	s_mov_b32 s50, m0
	s_mov_b32 m0, s49
	s_nop 0
	global_load_lds_dwordx4 v[78:79], off
	s_mov_b32 m0, s50
	v_lshl_add_u64 v[78:79], v[172:173], 0, s[18:19]
	s_mov_b32 s49, m0
	s_mov_b32 m0, s80
	s_nop 0
	global_load_lds_dwordx4 v[78:79], off
	s_mov_b32 m0, s49
	v_add_f32_e32 v215, v227, v130
	s_waitcnt lgkmcnt(14)
	v_mfma_f32_32x32x16_bf16 v[18:33], v[158:161], v[142:145], v[18:33]
	v_exp_f32_e32 v114, v114
	v_exp_f32_e32 v115, v115
	v_exp_f32_e32 v116, v116
	v_exp_f32_e32 v117, v117
	s_waitcnt lgkmcnt(12)
	v_mfma_f32_32x32x16_bf16 v[34:49], v[158:161], v[82:85], v[34:49]
	v_exp_f32_e32 v118, v118
	v_exp_f32_e32 v119, v119
	v_exp_f32_e32 v120, v120
	v_exp_f32_e32 v121, v121
	ds_read_b128 v[78:81], v214
	ds_read_b128 v[82:85], v214 offset:512
	s_waitcnt lgkmcnt(12)
	v_mfma_f32_32x32x16_bf16 v[18:33], v[154:157], v[86:89], v[18:33]
	v_exp_f32_e32 v122, v122
	v_exp_f32_e32 v123, v123
	v_exp_f32_e32 v124, v124
	v_exp_f32_e32 v125, v125
	ds_read_b128 v[86:89], v214 offset:2048
	ds_read_b128 v[228:231], v214 offset:2560
	s_waitcnt lgkmcnt(12)
	v_mfma_f32_32x32x16_bf16 v[34:49], v[154:157], v[90:93], v[34:49]
	v_exp_f32_e32 v126, v126
	v_exp_f32_e32 v127, v127
	v_exp_f32_e32 v128, v128
	v_exp_f32_e32 v129, v129
	s_waitcnt lgkmcnt(10)
	v_mfma_f32_32x32x16_bf16 v[18:33], v[150:153], v[94:97], v[18:33]
	v_exp_f32_e32 v98, v98
	v_exp_f32_e32 v99, v99
	v_exp_f32_e32 v100, v100
	v_exp_f32_e32 v101, v101
	s_waitcnt lgkmcnt(8)
	v_mfma_f32_32x32x16_bf16 v[34:49], v[150:153], v[66:69], v[34:49]
	v_exp_f32_e32 v102, v102
	v_exp_f32_e32 v103, v103
	v_exp_f32_e32 v104, v104
	v_exp_f32_e32 v105, v105
	s_waitcnt lgkmcnt(6)
	v_mfma_f32_32x32x16_bf16 v[18:33], v[146:149], v[70:73], v[18:33]
	v_exp_f32_e32 v106, v106
	v_exp_f32_e32 v107, v107
	v_exp_f32_e32 v108, v108
	v_exp_f32_e32 v109, v109
	s_waitcnt lgkmcnt(4)
	v_mfma_f32_32x32x16_bf16 v[34:49], v[146:149], v[74:77], v[34:49]
	v_exp_f32_e32 v110, v110
	v_exp_f32_e32 v111, v111
	v_exp_f32_e32 v112, v112
	v_exp_f32_e32 v113, v113
	s_waitcnt vmcnt(2) lgkmcnt(0)
	s_barrier
;   #define RESC() do{ if(!FIXREF&&resc){ asm volatile("s_waitcnt lgkmcnt(0)":::"memory"); \
;       _Pragma("unroll") for(int d_=0;d_<2;++d_) _Pragma("unroll") for(int r=0;r<16;++r)o[d_][r]*=wsf[crow(r,hi)]; } }while(0)
;   #define ROT() do{sl_prev=sl_cur;sl_cur=sl_next;sl_next=(sl_next==(NSLOT-1)*SLOTB)?0:sl_next+SLOTB;}while(0)
;   #define ENDW(tt) do{ if((tt)+3<NT){WAIT_BAR(2);} else if((tt)+2<NT){WAIT_BAR(1);} else {WAIT_BAR(0);} }while(0)
; template<int THRL,bool FIXREF,bool HALFK> __device__ __forceinline__ void attn_unit(float mref,long rowbase,int q0,const bf16*Qh,int PQ,const bf16*__restrict__ Kh_,int PK,const bf16*__restrict__ Vh_,int PV,bf16*Oh,int PO,const bf16*Gh,int PG,u32x4(&okeep)[4],int omode,float lam,float oml,const float ...
;     ...
;     STEP(pA0,pA1,pB0,pB1,t+1,(t+4<NT),(t+2<NT),(t+2<NT));     ENDW(t+1); RESC(); ROT();
	ds_read_b64_tr_b16 v[90:91], v213 offset:40960
	ds_read_b64_tr_b16 v[92:93], v213 offset:41472
	v_add_f32_e32 v66, v114, v115
	v_add_f32_e32 v66, v116, v66
	v_add_f32_e32 v66, v117, v66
	v_add_f32_e32 v66, v118, v66
	v_add_f32_e32 v66, v119, v66
	v_cvt_pk_bf16_f32 v158, v114, v115
	v_cvt_pk_bf16_f32 v159, v116, v117
	s_waitcnt lgkmcnt(5)
	v_mfma_f32_32x32x16_bf16 v[130:145], v[78:81], v[166:169], v[50:65]
	ds_read_b64_tr_b16 v[94:95], v213 offset:45056
	ds_read_b64_tr_b16 v[96:97], v213 offset:45568
	v_add_f32_e32 v66, v120, v66
	v_add_f32_e32 v66, v121, v66
	v_add_f32_e32 v66, v122, v66
	v_add_f32_e32 v114, v123, v66
	s_waitcnt lgkmcnt(6)
	v_mfma_f32_32x32x16_bf16 v[66:81], v[82:85], v[166:169], v[50:65]
	v_cvt_pk_bf16_f32 v160, v118, v119
	v_cvt_pk_bf16_f32 v161, v120, v121
	ds_read_b64_tr_b16 v[82:83], v213 offset:41984
	ds_read_b64_tr_b16 v[84:85], v213 offset:42496
	s_waitcnt lgkmcnt(7)
	v_mfma_f32_32x32x16_bf16 v[130:145], v[86:89], v[162:165], v[130:145]
	v_add_f32_e32 v86, v124, v114
	v_add_f32_e32 v86, v125, v86
	v_add_f32_e32 v86, v126, v86
	v_add_f32_e32 v114, v127, v86
	v_cvt_pk_bf16_f32 v154, v122, v123
	v_cvt_pk_bf16_f32 v155, v124, v125
	ds_read_b64_tr_b16 v[86:87], v213 offset:46080
	ds_read_b64_tr_b16 v[88:89], v213 offset:46592
	s_waitcnt lgkmcnt(8)
	v_mfma_f32_32x32x16_bf16 v[66:81], v[228:231], v[162:165], v[66:81]
	v_add_f32_e32 v114, v128, v114
	v_add_f32_e32 v114, v129, v114
	v_add_f32_e32 v114, v98, v114
	v_add_f32_e32 v118, v99, v114
	v_cvt_pk_bf16_f32 v156, v126, v127
	v_cvt_pk_bf16_f32 v157, v128, v129
	ds_read_b64_tr_b16 v[114:115], v213 offset:43008
	ds_read_b64_tr_b16 v[116:117], v213 offset:43520
	v_add_f32_e32 v118, v100, v118
	v_add_f32_e32 v118, v101, v118
	v_add_f32_e32 v118, v102, v118
	v_add_f32_e32 v118, v103, v118
	v_cvt_pk_bf16_f32 v150, v98, v99
	v_cvt_pk_bf16_f32 v151, v100, v101
	ds_read_b64_tr_b16 v[98:99], v213 offset:47104
	ds_read_b64_tr_b16 v[100:101], v213 offset:47616
	v_add_f32_e32 v118, v104, v118
	v_add_f32_e32 v118, v105, v118
	v_add_f32_e32 v118, v106, v118
	v_add_f32_e32 v118, v107, v118
	v_cvt_pk_bf16_f32 v152, v102, v103
	v_cvt_pk_bf16_f32 v153, v104, v105
	ds_read_b64_tr_b16 v[102:103], v213 offset:44032
	ds_read_b64_tr_b16 v[104:105], v213 offset:44544
	v_add_f32_e32 v118, v108, v118
	v_add_f32_e32 v118, v109, v118
	v_add_f32_e32 v118, v110, v118
	v_add_f32_e32 v118, v111, v118
	v_cvt_pk_bf16_f32 v146, v106, v107
	v_cvt_pk_bf16_f32 v147, v108, v109
	ds_read_b64_tr_b16 v[106:107], v213 offset:48128
	ds_read_b64_tr_b16 v[108:109], v213 offset:48640
	v_add_f32_e32 v118, v112, v118
	v_add_f32_e32 v118, v113, v118
	v_add_f32_e32 v118, 0, v118
	v_cvt_pk_bf16_f32 v148, v110, v111
	v_cvt_pk_bf16_f32 v149, v112, v113
	s_mov_b64 s[50:51], 0x1f8000
	v_lshl_add_u64 v[110:111], v[174:175], 0, s[50:51]
	s_mov_b32 s49, m0
	s_mov_b32 m0, s81
	s_nop 0
	global_load_lds_dwordx4 v[110:111], off
	s_mov_b32 m0, s49
	v_lshl_add_u64 v[110:111], v[172:173], 0, s[6:7]
	s_add_i32 s49, s48, 0x8000
	s_mov_b32 s50, m0
	s_mov_b32 m0, s49
	s_nop 0
	global_load_lds_dwordx4 v[110:111], off
	s_mov_b32 m0, s50
	v_add_f32_e32 v215, v215, v118
	s_waitcnt lgkmcnt(14)
	v_mfma_f32_32x32x16_bf16 v[18:33], v[158:161], v[90:93], v[18:33]
	v_exp_f32_e32 v130, v130
	v_exp_f32_e32 v131, v131
	v_exp_f32_e32 v132, v132
	v_exp_f32_e32 v133, v133
	s_waitcnt lgkmcnt(12)
	v_mfma_f32_32x32x16_bf16 v[34:49], v[158:161], v[94:97], v[34:49]
	v_exp_f32_e32 v134, v134
	v_exp_f32_e32 v135, v135
	v_exp_f32_e32 v136, v136
	v_exp_f32_e32 v137, v137
	ds_read_b128 v[90:93], v214 offset:8192
	ds_read_b128 v[110:113], v214 offset:8704
	s_waitcnt lgkmcnt(12)
	v_mfma_f32_32x32x16_bf16 v[18:33], v[154:157], v[82:85], v[18:33]
	v_exp_f32_e32 v138, v138
	v_exp_f32_e32 v139, v139
	v_exp_f32_e32 v140, v140
	v_exp_f32_e32 v141, v141
	ds_read_b128 v[228:231], v214 offset:10240
	ds_read_b128 v[232:235], v214 offset:10752
	s_waitcnt lgkmcnt(12)
	v_mfma_f32_32x32x16_bf16 v[34:49], v[154:157], v[86:89], v[34:49]
	v_exp_f32_e32 v142, v142
	v_exp_f32_e32 v143, v143
	v_exp_f32_e32 v144, v144
	v_exp_f32_e32 v145, v145
	s_waitcnt lgkmcnt(10)
	v_mfma_f32_32x32x16_bf16 v[18:33], v[150:153], v[114:117], v[18:33]
	v_exp_f32_e32 v66, v66
	v_exp_f32_e32 v67, v67
	v_exp_f32_e32 v68, v68
	v_exp_f32_e32 v69, v69
	s_waitcnt lgkmcnt(8)
	v_mfma_f32_32x32x16_bf16 v[34:49], v[150:153], v[98:101], v[34:49]
	v_exp_f32_e32 v70, v70
	v_exp_f32_e32 v71, v71
	v_exp_f32_e32 v72, v72
	v_exp_f32_e32 v73, v73
	s_waitcnt lgkmcnt(6)
	v_mfma_f32_32x32x16_bf16 v[18:33], v[146:149], v[102:105], v[18:33]
	v_exp_f32_e32 v74, v74
	v_exp_f32_e32 v75, v75
	v_exp_f32_e32 v76, v76
	v_exp_f32_e32 v77, v77
	s_waitcnt lgkmcnt(4)
	v_mfma_f32_32x32x16_bf16 v[34:49], v[146:149], v[106:109], v[34:49]
	v_exp_f32_e32 v78, v78
	v_exp_f32_e32 v79, v79
	v_exp_f32_e32 v80, v80
	v_exp_f32_e32 v81, v81
	s_waitcnt vmcnt(2) lgkmcnt(0)
	s_barrier
;   #define RESC() do{ if(!FIXREF&&resc){ asm volatile("s_waitcnt lgkmcnt(0)":::"memory"); \
;       _Pragma("unroll") for(int d_=0;d_<2;++d_) _Pragma("unroll") for(int r=0;r<16;++r)o[d_][r]*=wsf[crow(r,hi)]; } }while(0)
;   #define ROT() do{sl_prev=sl_cur;sl_cur=sl_next;sl_next=(sl_next==(NSLOT-1)*SLOTB)?0:sl_next+SLOTB;}while(0)
;   #define ENDW(tt) do{ if((tt)+3<NT){WAIT_BAR(2);} else if((tt)+2<NT){WAIT_BAR(1);} else {WAIT_BAR(0);} }while(0)
; template<int THRL,bool FIXREF,bool HALFK> __device__ __forceinline__ void attn_unit(float mref,long rowbase,int q0,const bf16*Qh,int PQ,const bf16*__restrict__ Kh_,int PK,const bf16*__restrict__ Vh_,int PV,bf16*Oh,int PO,const bf16*Gh,int PG,u32x4(&okeep)[4],int omode,float lam,float oml,const float ...
;     ...
;     STEP(pA0,pA1,pB0,pB1,t+1,(t+4<NT),(t+2<NT),(t+2<NT));     ENDW(t+1); RESC(); ROT();
	ds_read_b64_tr_b16 v[98:99], v213 offset:24576
	ds_read_b64_tr_b16 v[100:101], v213 offset:25088
	v_add_f32_e32 v82, v130, v131
	v_add_f32_e32 v82, v132, v82
	v_add_f32_e32 v82, v133, v82
	v_add_f32_e32 v82, v134, v82
	v_add_f32_e32 v82, v135, v82
	v_cvt_pk_bf16_f32 v158, v130, v131
	v_cvt_pk_bf16_f32 v159, v132, v133
	s_waitcnt lgkmcnt(5)
	v_mfma_f32_32x32x16_bf16 v[114:129], v[90:93], v[166:169], v[50:65]
	ds_read_b64_tr_b16 v[102:103], v213 offset:28672
	ds_read_b64_tr_b16 v[104:105], v213 offset:29184
	v_add_f32_e32 v82, v136, v82
	v_add_f32_e32 v82, v137, v82
	v_add_f32_e32 v82, v138, v82
	v_add_f32_e32 v130, v139, v82
	v_cvt_pk_bf16_f32 v160, v134, v135
	v_cvt_pk_bf16_f32 v161, v136, v137
	s_waitcnt lgkmcnt(6)
	v_mfma_f32_32x32x16_bf16 v[82:97], v[110:113], v[166:169], v[50:65]
	ds_read_b64_tr_b16 v[106:107], v213 offset:25600
	ds_read_b64_tr_b16 v[108:109], v213 offset:26112
	v_add_f32_e32 v110, v140, v130
	v_add_f32_e32 v110, v141, v110
	v_add_f32_e32 v110, v142, v110
	v_add_f32_e32 v130, v143, v110
	v_cvt_pk_bf16_f32 v154, v138, v139
	v_cvt_pk_bf16_f32 v155, v140, v141
	s_waitcnt lgkmcnt(7)
	v_mfma_f32_32x32x16_bf16 v[114:129], v[228:231], v[162:165], v[114:129]
	ds_read_b64_tr_b16 v[110:111], v213 offset:29696
	ds_read_b64_tr_b16 v[112:113], v213 offset:30208
	v_add_f32_e32 v130, v144, v130
	v_add_f32_e32 v130, v145, v130
	v_add_f32_e32 v130, v66, v130
	v_add_f32_e32 v134, v67, v130
	v_cvt_pk_bf16_f32 v156, v142, v143
	v_cvt_pk_bf16_f32 v157, v144, v145
	s_waitcnt lgkmcnt(8)
	v_mfma_f32_32x32x16_bf16 v[82:97], v[232:235], v[162:165], v[82:97]
	ds_read_b64_tr_b16 v[130:131], v213 offset:26624
	ds_read_b64_tr_b16 v[132:133], v213 offset:27136
	v_add_f32_e32 v134, v68, v134
	v_add_f32_e32 v134, v69, v134
	v_add_f32_e32 v134, v70, v134
	v_add_f32_e32 v134, v71, v134
	v_cvt_pk_bf16_f32 v150, v66, v67
	v_cvt_pk_bf16_f32 v151, v68, v69
	ds_read_b64_tr_b16 v[66:67], v213 offset:30720
	ds_read_b64_tr_b16 v[68:69], v213 offset:31232
	v_add_f32_e32 v134, v72, v134
	v_add_f32_e32 v134, v73, v134
	v_add_f32_e32 v134, v74, v134
	v_add_f32_e32 v134, v75, v134
	v_cvt_pk_bf16_f32 v152, v70, v71
	v_cvt_pk_bf16_f32 v153, v72, v73
	ds_read_b64_tr_b16 v[70:71], v213 offset:27648
	ds_read_b64_tr_b16 v[72:73], v213 offset:28160
	v_add_f32_e32 v134, v76, v134
	v_add_f32_e32 v134, v77, v134
	v_add_f32_e32 v134, v78, v134
	v_add_f32_e32 v134, v79, v134
	v_cvt_pk_bf16_f32 v146, v74, v75
	v_cvt_pk_bf16_f32 v147, v76, v77
	ds_read_b64_tr_b16 v[74:75], v213 offset:31744
	ds_read_b64_tr_b16 v[76:77], v213 offset:32256
	v_add_f32_e32 v134, v80, v134
	v_add_f32_e32 v134, v81, v134
	v_add_f32_e32 v134, 0, v134
	v_cvt_pk_bf16_f32 v148, v78, v79
	v_cvt_pk_bf16_f32 v149, v80, v81
	v_lshl_add_u64 v[78:79], v[172:173], 0, s[94:95]
	s_add_i32 s48, s48, 0xa000
	s_mov_b32 s49, m0
	s_mov_b32 m0, s48
	s_nop 0
	global_load_lds_dwordx4 v[78:79], off
	s_mov_b32 m0, s49
	v_add_f32_e32 v174, v215, v134
	s_waitcnt lgkmcnt(14)
	v_mfma_f32_32x32x16_bf16 v[18:33], v[158:161], v[98:101], v[18:33]
	v_exp_f32_e32 v114, v114
	v_exp_f32_e32 v115, v115
	v_exp_f32_e32 v116, v116
	v_exp_f32_e32 v117, v117
	s_waitcnt lgkmcnt(12)
	v_mfma_f32_32x32x16_bf16 v[34:49], v[158:161], v[102:105], v[34:49]
	v_exp_f32_e32 v118, v118
	v_exp_f32_e32 v119, v119
	v_exp_f32_e32 v120, v120
	v_exp_f32_e32 v121, v121
	ds_read_b128 v[78:81], v214 offset:16384
	ds_read_b128 v[134:137], v214 offset:16896
	s_waitcnt lgkmcnt(12)
	v_mfma_f32_32x32x16_bf16 v[18:33], v[154:157], v[106:109], v[18:33]
	v_exp_f32_e32 v122, v122
	v_exp_f32_e32 v123, v123
	v_exp_f32_e32 v124, v124
	v_exp_f32_e32 v125, v125
	ds_read_b128 v[138:141], v214 offset:18432
	ds_read_b128 v[142:145], v214 offset:18944
	s_waitcnt lgkmcnt(12)
	v_mfma_f32_32x32x16_bf16 v[34:49], v[154:157], v[110:113], v[34:49]
	v_exp_f32_e32 v126, v126
	v_exp_f32_e32 v127, v127
	v_exp_f32_e32 v128, v128
	v_exp_f32_e32 v129, v129
	s_waitcnt lgkmcnt(10)
	v_mfma_f32_32x32x16_bf16 v[18:33], v[150:153], v[130:133], v[18:33]
	v_exp_f32_e32 v82, v82
	v_exp_f32_e32 v83, v83
	v_exp_f32_e32 v84, v84
	v_exp_f32_e32 v85, v85
	s_waitcnt lgkmcnt(8)
	v_mfma_f32_32x32x16_bf16 v[34:49], v[150:153], v[66:69], v[34:49]
	v_exp_f32_e32 v86, v86
	v_exp_f32_e32 v87, v87
	v_exp_f32_e32 v88, v88
	v_exp_f32_e32 v89, v89
	s_waitcnt lgkmcnt(6)
	v_mfma_f32_32x32x16_bf16 v[18:33], v[146:149], v[70:73], v[18:33]
	v_exp_f32_e32 v90, v90
	v_exp_f32_e32 v91, v91
	v_exp_f32_e32 v92, v92
	v_exp_f32_e32 v93, v93
	s_waitcnt lgkmcnt(4)
	v_mfma_f32_32x32x16_bf16 v[34:49], v[146:149], v[74:77], v[34:49]
	v_exp_f32_e32 v94, v94
	v_exp_f32_e32 v95, v95
	v_exp_f32_e32 v96, v96
	v_exp_f32_e32 v97, v97
	s_waitcnt vmcnt(1) lgkmcnt(0)
	s_barrier
;   #define RESC() do{ if(!FIXREF&&resc){ asm volatile("s_waitcnt lgkmcnt(0)":::"memory"); \
;       _Pragma("unroll") for(int d_=0;d_<2;++d_) _Pragma("unroll") for(int r=0;r<16;++r)o[d_][r]*=wsf[crow(r,hi)]; } }while(0)
;   #define ROT() do{sl_prev=sl_cur;sl_cur=sl_next;sl_next=(sl_next==(NSLOT-1)*SLOTB)?0:sl_next+SLOTB;}while(0)
;   #define ENDW(tt) do{ if((tt)+3<NT){WAIT_BAR(2);} else if((tt)+2<NT){WAIT_BAR(1);} else {WAIT_BAR(0);} }while(0)
; template<int THRL,bool FIXREF,bool HALFK> __device__ __forceinline__ void attn_unit(float mref,long rowbase,int q0,const bf16*Qh,int PQ,const bf16*__restrict__ Kh_,int PK,const bf16*__restrict__ Vh_,int PV,bf16*Oh,int PO,const bf16*Gh,int PG,u32x4(&okeep)[4],int omode,float lam,float oml,const float ...
;     ...
;     STEP(pA0,pA1,pB0,pB1,t+1,(t+4<NT),(t+2<NT),(t+2<NT));     ENDW(t+1); RESC(); ROT();
	ds_read_b64_tr_b16 v[130:131], v213 offset:32768
	ds_read_b64_tr_b16 v[132:133], v213 offset:33280
	v_add_f32_e32 v66, v114, v115
	v_add_f32_e32 v66, v116, v66
	v_add_f32_e32 v66, v117, v66
	v_add_f32_e32 v66, v118, v66
	v_add_f32_e32 v66, v119, v66
	v_cvt_pk_bf16_f32 v158, v114, v115
	v_cvt_pk_bf16_f32 v159, v116, v117
	s_waitcnt lgkmcnt(5)
	v_mfma_f32_32x32x16_bf16 v[98:113], v[78:81], v[166:169], v[50:65]
	ds_read_b64_tr_b16 v[114:115], v213 offset:36864
	ds_read_b64_tr_b16 v[116:117], v213 offset:37376
	v_add_f32_e32 v66, v120, v66
	v_add_f32_e32 v66, v121, v66
	v_add_f32_e32 v66, v122, v66
	v_add_f32_e32 v146, v123, v66
	s_waitcnt lgkmcnt(6)
	v_mfma_f32_32x32x16_bf16 v[66:81], v[134:137], v[166:169], v[50:65]
	v_cvt_pk_bf16_f32 v160, v118, v119
	v_cvt_pk_bf16_f32 v161, v120, v121
	ds_read_b64_tr_b16 v[118:119], v213 offset:33792
	ds_read_b64_tr_b16 v[120:121], v213 offset:34304
	v_add_f32_e32 v134, v124, v146
	v_add_f32_e32 v134, v125, v134
	v_add_f32_e32 v134, v126, v134
	s_waitcnt lgkmcnt(7)
	v_mfma_f32_32x32x16_bf16 v[98:113], v[138:141], v[162:165], v[98:113]
	v_add_f32_e32 v138, v127, v134
	v_cvt_pk_bf16_f32 v154, v122, v123
	v_cvt_pk_bf16_f32 v155, v124, v125
	ds_read_b64_tr_b16 v[134:135], v213 offset:37888
	ds_read_b64_tr_b16 v[136:137], v213 offset:38400
	s_waitcnt lgkmcnt(8)
	v_mfma_f32_32x32x16_bf16 v[66:81], v[142:145], v[162:165], v[66:81]
	v_add_f32_e32 v122, v128, v138
	v_add_f32_e32 v122, v129, v122
	v_add_f32_e32 v122, v82, v122
	v_add_f32_e32 v122, v83, v122
	v_cvt_pk_bf16_f32 v156, v126, v127
	v_cvt_pk_bf16_f32 v157, v128, v129
	ds_read_b64_tr_b16 v[124:125], v213 offset:34816
	ds_read_b64_tr_b16 v[126:127], v213 offset:35328
	v_add_f32_e32 v122, v84, v122
	v_add_f32_e32 v122, v85, v122
	v_add_f32_e32 v122, v86, v122
	v_add_f32_e32 v122, v87, v122
	v_cvt_pk_bf16_f32 v150, v82, v83
	v_cvt_pk_bf16_f32 v151, v84, v85
	ds_read_b64_tr_b16 v[82:83], v213 offset:38912
	ds_read_b64_tr_b16 v[84:85], v213 offset:39424
	v_add_f32_e32 v122, v88, v122
	v_add_f32_e32 v122, v89, v122
	v_add_f32_e32 v122, v90, v122
	v_add_f32_e32 v122, v91, v122
	v_cvt_pk_bf16_f32 v152, v86, v87
	v_cvt_pk_bf16_f32 v153, v88, v89
	ds_read_b64_tr_b16 v[86:87], v213 offset:35840
	ds_read_b64_tr_b16 v[88:89], v213 offset:36352
	v_add_f32_e32 v122, v92, v122
	v_add_f32_e32 v122, v93, v122
	v_add_f32_e32 v122, v94, v122
	v_add_f32_e32 v122, v95, v122
	v_cvt_pk_bf16_f32 v146, v90, v91
	v_cvt_pk_bf16_f32 v147, v92, v93
	ds_read_b64_tr_b16 v[90:91], v213 offset:39936
	ds_read_b64_tr_b16 v[92:93], v213 offset:40448
	v_add_f32_e32 v122, v96, v122
	v_add_f32_e32 v122, v97, v122
	v_add_f32_e32 v122, 0, v122
	v_cvt_pk_bf16_f32 v148, v94, v95
	v_cvt_pk_bf16_f32 v149, v96, v97
	v_lshl_add_u64 v[94:95], v[172:173], 0, s[26:27]
	s_mov_b32 s48, m0
	s_mov_b32 m0, s80
	s_nop 0
	global_load_lds_dwordx4 v[94:95], off
	s_mov_b32 m0, s48
	v_add_f32_e32 v122, v174, v122
	s_waitcnt lgkmcnt(14)
	v_mfma_f32_32x32x16_bf16 v[18:33], v[158:161], v[130:133], v[18:33]
	v_exp_f32_e32 v98, v98
	v_exp_f32_e32 v99, v99
	v_exp_f32_e32 v100, v100
	v_exp_f32_e32 v101, v101
	s_waitcnt lgkmcnt(12)
	v_mfma_f32_32x32x16_bf16 v[34:49], v[158:161], v[114:117], v[34:49]
	v_exp_f32_e32 v102, v102
	v_exp_f32_e32 v103, v103
	v_exp_f32_e32 v104, v104
	v_exp_f32_e32 v105, v105
	ds_read_b128 v[128:131], v214
	ds_read_b128 v[138:141], v214 offset:512
	s_waitcnt lgkmcnt(12)
	v_mfma_f32_32x32x16_bf16 v[18:33], v[154:157], v[118:121], v[18:33]
	v_exp_f32_e32 v106, v106
	v_exp_f32_e32 v107, v107
	v_exp_f32_e32 v108, v108
	v_exp_f32_e32 v109, v109
	ds_read_b128 v[142:145], v214 offset:2048
	ds_read_b128 v[172:175], v214 offset:2560
	s_waitcnt lgkmcnt(12)
	v_mfma_f32_32x32x16_bf16 v[34:49], v[154:157], v[134:137], v[34:49]
	v_exp_f32_e32 v110, v110
	v_exp_f32_e32 v111, v111
	v_exp_f32_e32 v112, v112
	v_exp_f32_e32 v113, v113
	s_waitcnt lgkmcnt(10)
	v_mfma_f32_32x32x16_bf16 v[18:33], v[150:153], v[124:127], v[18:33]
	v_exp_f32_e32 v66, v66
	v_exp_f32_e32 v67, v67
	v_exp_f32_e32 v68, v68
	v_exp_f32_e32 v69, v69
	s_waitcnt lgkmcnt(8)
	v_mfma_f32_32x32x16_bf16 v[34:49], v[150:153], v[82:85], v[34:49]
	v_exp_f32_e32 v70, v70
	v_exp_f32_e32 v71, v71
	v_exp_f32_e32 v72, v72
	v_exp_f32_e32 v73, v73
	s_waitcnt lgkmcnt(6)
	v_mfma_f32_32x32x16_bf16 v[18:33], v[146:149], v[86:89], v[18:33]
	v_exp_f32_e32 v74, v74
	v_exp_f32_e32 v75, v75
	v_exp_f32_e32 v76, v76
	v_exp_f32_e32 v77, v77
	s_waitcnt lgkmcnt(4)
	v_mfma_f32_32x32x16_bf16 v[34:49], v[146:149], v[90:93], v[34:49]
	v_exp_f32_e32 v78, v78
	v_exp_f32_e32 v79, v79
	v_exp_f32_e32 v80, v80
	v_exp_f32_e32 v81, v81
	s_waitcnt vmcnt(0) lgkmcnt(0)
	s_barrier
;   #define RESC() do{ if(!FIXREF&&resc){ asm volatile("s_waitcnt lgkmcnt(0)":::"memory"); \
;       _Pragma("unroll") for(int d_=0;d_<2;++d_) _Pragma("unroll") for(int r=0;r<16;++r)o[d_][r]*=wsf[crow(r,hi)]; } }while(0)
;   #define PKW(P,B) cvtpk_s(P[B],P[B+1])
; template<int THRL,bool FIXREF,bool HALFK> __device__ __forceinline__ void attn_unit(float mref,long rowbase,int q0,const bf16*Qh,int PQ,const bf16*__restrict__ Kh_,int PK,const bf16*__restrict__ Vh_,int PV,bf16*Oh,int PO,const bf16*Gh,int PG,u32x4(&okeep)[4],int omode,float lam,float oml,const float ...
;     ...
;   STEP(pB0,pB1,pA0,pA1,NT-1,false,false,false); RESC();
;   { float sacc=pB0[0]+pB0[1]; _Pragma("unroll") for(int r=2;r<16;++r)sacc+=pB0[r]; _Pragma("unroll") for(int r=0;r<16;++r)sacc+=pB1[r]; l_reg+=sacc;
;     pw0=(u32x4){PKW(pB0,0),PKW(pB0,2),PKW(pB0,4),PKW(pB0,6)};pw1=(u32x4){PKW(pB0,8),PKW(pB0,10),PKW(pB0,12),PKW(pB0,14)};pw2=(u32x4){PKW(pB1,0),PKW(pB1,2),PKW(pB1,4),PKW(pB1,6)};pw3=(u32x4){PKW(pB1,8),PKW(pB1,10),PKW(pB1,12),PKW(pB1,14)};
	ds_read_b64_tr_b16 v[114:115], v213 offset:40960
	ds_read_b64_tr_b16 v[116:117], v213 offset:41472
	v_add_f32_e32 v82, v98, v99
	v_add_f32_e32 v82, v100, v82
	v_add_f32_e32 v82, v101, v82
	v_add_f32_e32 v82, v102, v82
	v_add_f32_e32 v118, v103, v82
	v_cvt_pk_bf16_f32 v158, v98, v99
	v_cvt_pk_bf16_f32 v159, v100, v101
	s_waitcnt lgkmcnt(5)
	v_mfma_f32_32x32x16_bf16 v[82:97], v[128:131], v[166:169], v[50:65]
	ds_read_b64_tr_b16 v[98:99], v213 offset:45056
	ds_read_b64_tr_b16 v[100:101], v213 offset:45568
	v_add_f32_e32 v118, v104, v118
	v_add_f32_e32 v118, v105, v118
	v_add_f32_e32 v118, v106, v118
	v_add_f32_e32 v123, v107, v118
	v_cvt_pk_bf16_f32 v160, v102, v103
	v_cvt_pk_bf16_f32 v161, v104, v105
	s_waitcnt lgkmcnt(6)
	v_mfma_f32_32x32x16_bf16 v[50:65], v[138:141], v[166:169], v[50:65]
	ds_read_b64_tr_b16 v[118:119], v213 offset:41984
	ds_read_b64_tr_b16 v[120:121], v213 offset:42496
	v_add_f32_e32 v102, v108, v123
	v_add_f32_e32 v102, v109, v102
	v_add_f32_e32 v102, v110, v102
	v_add_f32_e32 v123, v111, v102
	v_cvt_pk_bf16_f32 v154, v106, v107
	v_cvt_pk_bf16_f32 v155, v108, v109
	s_waitcnt lgkmcnt(7)
	v_mfma_f32_32x32x16_bf16 v[82:97], v[142:145], v[162:165], v[82:97]
	ds_read_b64_tr_b16 v[102:103], v213 offset:46080
	ds_read_b64_tr_b16 v[104:105], v213 offset:46592
	v_add_f32_e32 v106, v112, v123
	v_add_f32_e32 v106, v113, v106
	v_add_f32_e32 v106, v66, v106
	v_add_f32_e32 v123, v67, v106
	v_cvt_pk_bf16_f32 v156, v110, v111
	v_cvt_pk_bf16_f32 v157, v112, v113
	s_waitcnt lgkmcnt(8)
	v_mfma_f32_32x32x16_bf16 v[50:65], v[172:175], v[162:165], v[50:65]
	ds_read_b64_tr_b16 v[106:107], v213 offset:43008
	ds_read_b64_tr_b16 v[108:109], v213 offset:43520
	v_add_f32_e32 v110, v68, v123
	v_add_f32_e32 v110, v69, v110
	v_add_f32_e32 v110, v70, v110
	v_add_f32_e32 v110, v71, v110
	v_cvt_pk_bf16_f32 v150, v66, v67
	v_cvt_pk_bf16_f32 v151, v68, v69
	ds_read_b64_tr_b16 v[66:67], v213 offset:47104
	ds_read_b64_tr_b16 v[68:69], v213 offset:47616
	v_add_f32_e32 v110, v72, v110
	v_add_f32_e32 v110, v73, v110
	v_add_f32_e32 v110, v74, v110
	v_add_f32_e32 v123, v75, v110
	v_cvt_pk_bf16_f32 v152, v70, v71
	v_cvt_pk_bf16_f32 v153, v72, v73
	ds_read_b64_tr_b16 v[110:111], v213 offset:44032
	ds_read_b64_tr_b16 v[112:113], v213 offset:44544
	v_add_f32_e32 v70, v76, v123
	v_add_f32_e32 v70, v77, v70
	v_add_f32_e32 v70, v78, v70
	v_add_f32_e32 v123, v79, v70
	v_cvt_pk_bf16_f32 v146, v74, v75
	v_cvt_pk_bf16_f32 v147, v76, v77
	ds_read_b64_tr_b16 v[70:71], v213 offset:48128
	ds_read_b64_tr_b16 v[72:73], v213 offset:48640
	v_add_f32_e32 v74, v80, v123
	v_add_f32_e32 v74, v81, v74
	v_add_f32_e32 v74, 0, v74
	v_cvt_pk_bf16_f32 v148, v78, v79
	v_cvt_pk_bf16_f32 v149, v80, v81
	v_exp_f32_e32 v82, v82
	v_exp_f32_e32 v83, v83
	v_exp_f32_e32 v84, v84
	v_exp_f32_e32 v85, v85
	s_nop 0
	v_exp_f32_e32 v86, v86
	v_exp_f32_e32 v87, v87
	v_exp_f32_e32 v88, v88
	v_exp_f32_e32 v89, v89
	s_nop 0
	v_exp_f32_e32 v90, v90
	v_exp_f32_e32 v91, v91
	v_exp_f32_e32 v92, v92
	v_exp_f32_e32 v93, v93
	s_nop 0
	v_exp_f32_e32 v94, v94
	v_exp_f32_e32 v95, v95
	v_exp_f32_e32 v96, v96
	v_exp_f32_e32 v97, v97
	v_exp_f32_e32 v50, v50
	v_exp_f32_e32 v51, v51
	v_exp_f32_e32 v52, v52
	v_exp_f32_e32 v53, v53
	s_nop 0
	v_exp_f32_e32 v54, v54
	v_exp_f32_e32 v55, v55
	v_exp_f32_e32 v56, v56
	v_exp_f32_e32 v57, v57
	s_nop 0
	v_exp_f32_e32 v58, v58
	v_exp_f32_e32 v59, v59
	v_exp_f32_e32 v60, v60
	v_exp_f32_e32 v61, v61
	s_nop 0
	v_exp_f32_e32 v62, v62
	v_exp_f32_e32 v63, v63
	v_exp_f32_e32 v64, v64
	v_exp_f32_e32 v65, v65
	s_waitcnt lgkmcnt(14)
	v_mfma_f32_32x32x16_bf16 v[18:33], v[158:161], v[114:117], v[18:33]
	v_add_f32_e32 v75, v82, v83
	v_add_f32_e32 v75, v84, v75
	v_add_f32_e32 v75, v85, v75
	v_add_f32_e32 v75, v86, v75
	v_add_f32_e32 v75, v87, v75
	v_add_f32_e32 v75, v88, v75
	v_add_f32_e32 v75, v89, v75
	s_waitcnt lgkmcnt(12)
	v_mfma_f32_32x32x16_bf16 v[34:49], v[158:161], v[98:101], v[34:49]
	v_add_f32_e32 v75, v90, v75
	v_add_f32_e32 v75, v91, v75
	v_add_f32_e32 v75, v92, v75
	v_add_f32_e32 v75, v93, v75
	v_add_f32_e32 v75, v94, v75
	v_add_f32_e32 v75, v95, v75
	v_add_f32_e32 v75, v96, v75
	s_waitcnt lgkmcnt(10)
	v_mfma_f32_32x32x16_bf16 v[18:33], v[154:157], v[118:121], v[18:33]
	v_add_f32_e32 v75, v97, v75
	v_add_f32_e32 v75, v50, v75
	v_add_f32_e32 v75, v51, v75
	v_add_f32_e32 v75, v52, v75
	v_add_f32_e32 v75, v53, v75
	v_add_f32_e32 v75, v54, v75
	v_add_f32_e32 v75, v55, v75
	s_waitcnt lgkmcnt(8)
	v_mfma_f32_32x32x16_bf16 v[34:49], v[154:157], v[102:105], v[34:49]
	v_add_f32_e32 v75, v56, v75
	v_add_f32_e32 v75, v57, v75
	v_add_f32_e32 v75, v58, v75
	v_add_f32_e32 v75, v59, v75
	v_add_f32_e32 v75, v60, v75
	v_add_f32_e32 v75, v61, v75
	v_add_f32_e32 v75, v62, v75
	s_waitcnt lgkmcnt(6)
	v_mfma_f32_32x32x16_bf16 v[18:33], v[150:153], v[106:109], v[18:33]
	v_add_f32_e32 v75, v63, v75
	v_add_f32_e32 v75, v64, v75
	v_add_f32_e32 v75, v65, v75
	v_add_f32_e32 v74, v122, v74
	v_add_f32_e32 v74, v74, v75
	v_cvt_pk_bf16_f32 v76, v82, v83
	v_cvt_pk_bf16_f32 v77, v84, v85
	s_waitcnt lgkmcnt(4)
	v_mfma_f32_32x32x16_bf16 v[34:49], v[150:153], v[66:69], v[34:49]
	v_cvt_pk_bf16_f32 v78, v86, v87
	v_cvt_pk_bf16_f32 v79, v88, v89
	v_cvt_pk_bf16_f32 v80, v90, v91
	v_cvt_pk_bf16_f32 v81, v92, v93
	v_cvt_pk_bf16_f32 v82, v94, v95
	v_cvt_pk_bf16_f32 v83, v96, v97
	v_cvt_pk_bf16_f32 v50, v50, v51
	s_waitcnt lgkmcnt(2)
	v_mfma_f32_32x32x16_bf16 v[18:33], v[146:149], v[110:113], v[18:33]
	v_cvt_pk_bf16_f32 v51, v52, v53
	v_cvt_pk_bf16_f32 v52, v54, v55
	v_cvt_pk_bf16_f32 v53, v56, v57
	v_cvt_pk_bf16_f32 v54, v58, v59
	v_cvt_pk_bf16_f32 v55, v60, v61
	v_cvt_pk_bf16_f32 v56, v62, v63
	v_cvt_pk_bf16_f32 v57, v64, v65
	s_waitcnt lgkmcnt(0)
; __device__ __forceinline__ int crow(int r,int hi){return (r&3)+8*(r>>2)+4*hi;}
; #define SBAR() __builtin_amdgcn_sched_barrier(0)
; __device__ __forceinline__ void pv(f32x16*o,int vb,bf16x8 pa0,bf16x8 pa1,bf16x8 pa2,bf16x8 pa3){
;   #pragma unroll
;   for(int d0=0;d0<2;++d0){s16x4 lo[4],hi[4];
;     #pragma unroll
;     for(int ks=0;ks<4;++ks){
;       asm volatile("ds_read_b64_tr_b16 %0,%1 offset:%c2":"=&v"(lo[ks]):"v"(vb),"i"(d0*4096+ks*1024):"memory");
;       asm volatile("ds_read_b64_tr_b16 %0,%1 offset:%c2":"=&v"(hi[ks]):"v"(vb),"i"(d0*4096+ks*1024+512):"memory");}
;     asm volatile("s_waitcnt lgkmcnt(0)":::"memory");SBAR();
;     ...
;     o[d0]=__builtin_amdgcn_mfma_f32_32x32x16_bf16(pa0,PK(0),o[d0],0,0,0);
;     o[d0]=__builtin_amdgcn_mfma_f32_32x32x16_bf16(pa1,PK(1),o[d0],0,0,0);
;     o[d0]=__builtin_amdgcn_mfma_f32_32x32x16_bf16(pa2,PK(2),o[d0],0,0,0);
;     o[d0]=__builtin_amdgcn_mfma_f32_32x32x16_bf16(pa3,PK(3),o[d0],0,0,0);
;     ...
;   }
; }
; template<int THRL,bool FIXREF,bool HALFK> __device__ __forceinline__ void attn_unit(float mref,long rowbase,int q0,const bf16*Qh,int PQ,const bf16*__restrict__ Kh_,int PK,const bf16*__restrict__ Vh_,int PV,bf16*Oh,int PO,const bf16*Gh,int PG,u32x4(&okeep)[4],int omode,float lam,float oml,const float ...
;     ...
;     SBAR(); pv(o,vb0+sl_cur,PAF(0),PAF(1),PAF(2),PAF(3)); }
;     ...
;   {auto rr=__builtin_amdgcn_permlane32_swap(__float_as_uint(l_reg),__float_as_uint(l_reg),false,false);l_reg=__uint_as_float(rr[0])+__uint_as_float(rr[1]);}
;   if(hi==0)wsf[32+r32]=l_reg;asm volatile("s_waitcnt lgkmcnt(0)":::"memory");
;   float rli[16];
;   #pragma unroll
;   for(int r=0;r<16;++r)rli[r]=__builtin_amdgcn_rcpf(wsf[32+crow(r,hi)]);
;   bf16*Ow=Oh+(rowbase+q0+wid*QBLK)*PO;
;   { bf16*stg=(bf16*)(shm+LDS_OST)+wid*2048;
;     #pragma unroll
;     for(int r=0;r<16;++r){const int orow=crow(r,hi);
;       #pragma unroll
;       for(int d0=0;d0<2;++d0)stg[orow*64+d0*32+r32]=__float2bfloat16(o[d0][r]*rli[r]);}
;     asm volatile("s_waitcnt lgkmcnt(0)":::"memory");
	v_mfma_f32_32x32x16_bf16 v[34:49], v[146:149], v[70:73], v[34:49]
	ds_read_b64_tr_b16 v[58:59],v0 offset:0
	ds_read_b64_tr_b16 v[60:61],v0 offset:512
	ds_read_b64_tr_b16 v[62:63],v0 offset:1024
	ds_read_b64_tr_b16 v[64:65],v0 offset:1536
	ds_read_b64_tr_b16 v[66:67],v0 offset:2048
	ds_read_b64_tr_b16 v[68:69],v0 offset:2560
	ds_read_b64_tr_b16 v[70:71],v0 offset:3072
	ds_read_b64_tr_b16 v[72:73],v0 offset:3584
	s_waitcnt lgkmcnt(0)
	s_nop 0
	v_mfma_f32_32x32x16_bf16 v[18:33], v[76:79], v[58:61], v[18:33]
	ds_read_b64_tr_b16 v[58:59],v0 offset:4096
	ds_read_b64_tr_b16 v[60:61],v0 offset:4608
	v_mfma_f32_32x32x16_bf16 v[18:33], v[80:83], v[62:65], v[18:33]
	ds_read_b64_tr_b16 v[62:63],v0 offset:5120
	ds_read_b64_tr_b16 v[64:65],v0 offset:5632
	v_mfma_f32_32x32x16_bf16 v[18:33], v[50:53], v[66:69], v[18:33]
	ds_read_b64_tr_b16 v[66:67],v0 offset:6144
	ds_read_b64_tr_b16 v[68:69],v0 offset:6656
	v_mfma_f32_32x32x16_bf16 v[18:33], v[54:57], v[70:73], v[18:33]
	ds_read_b64_tr_b16 v[70:71],v0 offset:7168
	ds_read_b64_tr_b16 v[72:73],v0 offset:7680
	s_waitcnt lgkmcnt(0)
	v_mfma_f32_32x32x16_bf16 v[34:49], v[76:79], v[58:61], v[34:49]
	v_mov_b32_e32 v0, v74
	s_nop 1
	v_permlane32_swap_b32_e32 v74, v0
	v_cmp_gt_u32_e32 vcc, 32, v209
	v_mfma_f32_32x32x16_bf16 v[34:49], v[80:83], v[62:65], v[34:49]
	v_mfma_f32_32x32x16_bf16 v[34:49], v[50:53], v[66:69], v[34:49]
	v_mfma_f32_32x32x16_bf16 v[34:49], v[54:57], v[70:73], v[34:49]
	s_and_saveexec_b64 s[48:49], vcc
	v_lshl_add_u32 v50, v171, 2, s20
	v_add_f32_e32 v0, v74, v0
	ds_write_b32 v50, v0 offset:49280
	s_or_b64 exec, exec, s[48:49]
	s_waitcnt lgkmcnt(0)
	v_lshl_add_u32 v0, v212, 4, s20
	ds_read_b128 v[50:53], v0 offset:49280
	ds_read_b128 v[54:57], v0 offset:49312
	s_lshl_b32 s20, s79, 12
	s_add_i32 s20, s20, 0
	v_lshlrev_b32_e32 v66, 1, v171
	s_waitcnt lgkmcnt(1)
	v_rcp_f32_e32 v58, v50
	v_rcp_f32_e32 v59, v51
	v_rcp_f32_e32 v60, v52
	v_rcp_f32_e32 v61, v53
	s_waitcnt lgkmcnt(0)
	v_rcp_f32_e32 v62, v54
	ds_read_b128 v[50:53], v0 offset:49344
	v_rcp_f32_e32 v63, v55
	v_rcp_f32_e32 v64, v56
	v_rcp_f32_e32 v65, v57
	ds_read_b128 v[54:57], v0 offset:49376
	s_waitcnt lgkmcnt(1)
	v_rcp_f32_e32 v0, v50
	v_rcp_f32_e32 v50, v51
	v_rcp_f32_e32 v51, v52
	v_rcp_f32_e32 v52, v53
	s_waitcnt lgkmcnt(0)
	v_rcp_f32_e32 v53, v54
	v_rcp_f32_e32 v54, v55
	v_rcp_f32_e32 v55, v56
	v_rcp_f32_e32 v56, v57
	v_lshlrev_b32_e32 v57, 9, v212
	v_mul_f32_e32 v18, v18, v58
	v_add3_u32 v57, s20, v57, v66
	v_cvt_pk_bf16_f32 v18, v18, s0
	ds_write_b16 v57, v18 offset:51200
	v_mul_f32_e32 v18, v34, v58
	v_cvt_pk_bf16_f32 v18, v18, s0
	ds_write_b16 v57, v18 offset:51264
	v_mul_f32_e32 v18, v19, v59
	v_cvt_pk_bf16_f32 v18, v18, s0
	ds_write_b16 v57, v18 offset:51328
	v_mul_f32_e32 v18, v35, v59
	v_cvt_pk_bf16_f32 v18, v18, s0
	ds_write_b16 v57, v18 offset:51392
	v_mul_f32_e32 v18, v20, v60
	v_cvt_pk_bf16_f32 v18, v18, s0
	ds_write_b16 v57, v18 offset:51456
	v_mul_f32_e32 v18, v36, v60
	v_cvt_pk_bf16_f32 v18, v18, s0
	ds_write_b16 v57, v18 offset:51520
	v_mul_f32_e32 v18, v21, v61
	v_cvt_pk_bf16_f32 v18, v18, s0
	ds_write_b16 v57, v18 offset:51584
	v_mul_f32_e32 v18, v37, v61
	v_cvt_pk_bf16_f32 v18, v18, s0
	ds_write_b16 v57, v18 offset:51648
	v_mul_f32_e32 v18, v22, v62
	v_cvt_pk_bf16_f32 v18, v18, s0
	ds_write_b16 v57, v18 offset:52224
	v_mul_f32_e32 v18, v38, v62
	v_cvt_pk_bf16_f32 v18, v18, s0
	ds_write_b16 v57, v18 offset:52288
	v_mul_f32_e32 v18, v23, v63
	v_cvt_pk_bf16_f32 v18, v18, s0
	ds_write_b16 v57, v18 offset:52352
	v_mul_f32_e32 v18, v39, v63
	v_cvt_pk_bf16_f32 v18, v18, s0
	ds_write_b16 v57, v18 offset:52416
	v_mul_f32_e32 v18, v24, v64
	v_cvt_pk_bf16_f32 v18, v18, s0
	ds_write_b16 v57, v18 offset:52480
	v_mul_f32_e32 v18, v40, v64
	v_cvt_pk_bf16_f32 v18, v18, s0
	ds_write_b16 v57, v18 offset:52544
	v_mul_f32_e32 v18, v25, v65
	v_cvt_pk_bf16_f32 v18, v18, s0
	ds_write_b16 v57, v18 offset:52608
	v_mul_f32_e32 v18, v41, v65
	v_cvt_pk_bf16_f32 v18, v18, s0
	ds_write_b16 v57, v18 offset:52672
	v_mul_f32_e32 v18, v26, v0
	v_mul_f32_e32 v0, v42, v0
	v_cvt_pk_bf16_f32 v0, v0, s0
	ds_write_b16 v57, v0 offset:53312
	v_mul_f32_e32 v0, v27, v50
	v_cvt_pk_bf16_f32 v0, v0, s0
	ds_write_b16 v57, v0 offset:53376
	v_mul_f32_e32 v0, v43, v50
	v_cvt_pk_bf16_f32 v0, v0, s0
	ds_write_b16 v57, v0 offset:53440
	v_mul_f32_e32 v0, v28, v51
	v_cvt_pk_bf16_f32 v0, v0, s0
	ds_write_b16 v57, v0 offset:53504
	v_mul_f32_e32 v0, v44, v51
	v_cvt_pk_bf16_f32 v0, v0, s0
	ds_write_b16 v57, v0 offset:53568
	v_mul_f32_e32 v0, v29, v52
	v_cvt_pk_bf16_f32 v0, v0, s0
	ds_write_b16 v57, v0 offset:53632
	v_mul_f32_e32 v0, v45, v52
	v_cvt_pk_bf16_f32 v0, v0, s0
	ds_write_b16 v57, v0 offset:53696
	v_mul_f32_e32 v0, v30, v53
	v_cvt_pk_bf16_f32 v0, v0, s0
	ds_write_b16 v57, v0 offset:54272
	v_mul_f32_e32 v0, v46, v53
	v_cvt_pk_bf16_f32 v0, v0, s0
	ds_write_b16 v57, v0 offset:54336
	v_mul_f32_e32 v0, v31, v54
	v_cvt_pk_bf16_f32 v0, v0, s0
	ds_write_b16 v57, v0 offset:54400
	v_mul_f32_e32 v0, v47, v54
	v_cvt_pk_bf16_f32 v0, v0, s0
	ds_write_b16 v57, v0 offset:54464
	v_mul_f32_e32 v0, v32, v55
	v_cvt_pk_bf16_f32 v0, v0, s0
	ds_write_b16 v57, v0 offset:54528
	v_mul_f32_e32 v0, v48, v55
	v_cvt_pk_bf16_f32 v0, v0, s0
	ds_write_b16 v57, v0 offset:54592
	v_mul_f32_e32 v0, v33, v56
	v_cvt_pk_bf16_f32 v0, v0, s0
	ds_write_b16 v57, v0 offset:54656
	v_mul_f32_e32 v0, v49, v56
	v_cvt_pk_bf16_f32 v18, v18, s0
	v_cvt_pk_bf16_f32 v0, v0, s0
	ds_write_b16 v57, v18 offset:53248
	ds_write_b16 v57, v0 offset:54720
	s_lshl_b64 s[46:47], s[46:47], 11
	s_waitcnt lgkmcnt(0)
	s_add_u32 s46, s69, s46
	s_addc_u32 s47, s70, s47
	s_mov_b64 s[48:49], -1
	s_and_b64 vcc, exec, s[42:43]
	s_cbranch_vccz .LBB0_470
; __device__ __forceinline__ unsigned cvtpk_s(float lo,float hi){f32x2_t v={lo,hi};bf16x2_t b=__builtin_convertvector(v,bf16x2_t);return __builtin_bit_cast(unsigned,b);}
; template<int THRL,bool FIXREF,bool HALFK> __device__ __forceinline__ void attn_unit(float mref,long rowbase,int q0,const bf16*Qh,int PQ,const bf16*__restrict__ Kh_,int PK,const bf16*__restrict__ Vh_,int PV,bf16*Oh,int PO,const bf16*Gh,int PG,u32x4(&okeep)[4],int omode,float lam,float oml,const float ...
;     ...
;     else if(Gh){
;       u32x4 gv[4]; const char*gst=shm+LDS_GST+wid*4096+lane*16;
;       #pragma unroll
;       for(int i=0;i<4;++i) gv[i]=*(const u32x4*)(gst+i*1024);
;       #pragma unroll
;       for(int i=0;i<4;++i){const int row=i*8+(lane>>3),ch=lane&7; u32x4 v=*(const u32x4*)(stg+row*64+ch*8);
;         #pragma unroll
;         for(int k=0;k<4;++k){ const float g0=__uint_as_float(gv[i][k]<<16),g1=__uint_as_float(gv[i][k]&0xffff0000u),o0=__uint_as_float(v[k]<<16),o1=__uint_as_float(v[k]&0xffff0000u);
;           v[k]=cvtpk_s(o0*g0*__builtin_amdgcn_rcpf(1.f+__builtin_amdgcn_exp2f(-1.4426950408889634f*g0)),o1*g1*__builtin_amdgcn_rcpf(1.f+__builtin_amdgcn_exp2f(-1.4426950408889634f*g1))); }
;         ATTN_STORE16(Ow+(long)row*PO+ch*8,v);} }
	s_mov_b64 s[42:43], -1
	s_and_b64 vcc, exec, s[40:41]
	s_cbranch_vccz .LBB0_467
	v_lshl_add_u32 v0, v209, 4, s20
	v_add_u32_e32 v0, 0x14800, v0
	ds_read_b128 v[30:33], v0
	ds_read_b128 v[26:29], v0 offset:1024
	ds_read_b128 v[22:25], v0 offset:2048
	ds_read_b128 v[18:21], v0 offset:3072
	v_lshlrev_b32_e32 v0, 1, v211
	v_and_b32_e32 v0, 0x70, v0
	v_add_u32_e32 v36, s20, v0
	v_lshl_add_u64 v[34:35], s[46:47], 0, v[0:1]
	v_lshl_add_u32 v0, v208, 7, v36
	s_waitcnt lgkmcnt(3)
	v_lshlrev_b32_e32 v44, 16, v30
	ds_read_b128 v[38:41], v0 offset:51200
	v_mul_f32_e32 v0, 0xbfb8aa3b, v44
	v_exp_f32_e32 v0, v0
	v_and_b32_e32 v43, 0xffff0000, v30
	s_mov_b64 s[42:43], 0
	s_waitcnt lgkmcnt(0)
	v_lshlrev_b32_e32 v42, 16, v38
	v_add_f32_e32 v0, 1.0, v0
	v_rcp_f32_e32 v46, v0
	v_mul_f32_e32 v0, 0xbfb8aa3b, v43
	v_exp_f32_e32 v0, v0
	v_and_b32_e32 v45, 0xffff0000, v38
	v_lshlrev_b32_e32 v38, 16, v31
	v_pk_mul_f32 v[44:45], v[42:43], v[44:45]
	v_add_f32_e32 v0, 1.0, v0
	v_rcp_f32_e32 v47, v0
	v_mul_f32_e32 v0, 0xbfb8aa3b, v38
	v_exp_f32_e32 v0, v0
	v_pk_mul_f32 v[42:43], v[46:47], v[44:45]
	s_nop 0
	v_cvt_pk_bf16_f32 v30, v42, v43
	v_and_b32_e32 v43, 0xffff0000, v31
	v_add_f32_e32 v0, 1.0, v0
	v_rcp_f32_e32 v44, v0
	v_mul_f32_e32 v0, 0xbfb8aa3b, v43
	v_exp_f32_e32 v0, v0
	v_lshlrev_b32_e32 v42, 16, v39
	v_and_b32_e32 v39, 0xffff0000, v39
	v_pk_mul_f32 v[38:39], v[42:43], v[38:39]
	v_add_f32_e32 v0, 1.0, v0
	v_lshlrev_b32_e32 v42, 16, v32
	v_rcp_f32_e32 v45, v0
	v_mul_f32_e32 v0, 0xbfb8aa3b, v42
	v_exp_f32_e32 v0, v0
	v_and_b32_e32 v43, 0xffff0000, v40
	v_pk_mul_f32 v[38:39], v[44:45], v[38:39]
	v_add_f32_e32 v0, 1.0, v0
	v_cvt_pk_bf16_f32 v31, v38, v39
	v_and_b32_e32 v39, 0xffff0000, v32
	v_rcp_f32_e32 v44, v0
	v_mul_f32_e32 v0, 0xbfb8aa3b, v39
	v_exp_f32_e32 v0, v0
	v_lshlrev_b32_e32 v38, 16, v40
	v_lshlrev_b32_e32 v40, 16, v33
	v_pk_mul_f32 v[42:43], v[38:39], v[42:43]
	v_add_f32_e32 v0, 1.0, v0
	v_rcp_f32_e32 v45, v0
	v_mul_f32_e32 v0, 0xbfb8aa3b, v40
	v_exp_f32_e32 v0, v0
	v_pk_mul_f32 v[38:39], v[44:45], v[42:43]
	s_nop 0
	v_cvt_pk_bf16_f32 v32, v38, v39
	v_and_b32_e32 v39, 0xffff0000, v33
	v_add_f32_e32 v0, 1.0, v0
	v_rcp_f32_e32 v42, v0
	v_mul_f32_e32 v0, 0xbfb8aa3b, v39
	v_exp_f32_e32 v0, v0
	v_lshlrev_b32_e32 v38, 16, v41
	v_and_b32_e32 v41, 0xffff0000, v41
	v_pk_mul_f32 v[40:41], v[38:39], v[40:41]
	v_add_f32_e32 v0, 1.0, v0
	v_rcp_f32_e32 v43, v0
	v_lshlrev_b32_e32 v0, 11, v208
	v_pk_mul_f32 v[38:39], v[42:43], v[40:41]
	s_nop 0
	v_cvt_pk_bf16_f32 v33, v38, v39
	v_lshl_add_u64 v[38:39], v[34:35], 0, v[0:1]
	v_lshlrev_b32_e32 v40, 16, v26
	global_store_dwordx4 v[38:39], v[30:33], off
	v_and_b32_e32 v39, 0xffff0000, v26
	v_mul_f32_e32 v26, 0xbfb8aa3b, v40
	v_exp_f32_e32 v26, v26
	v_or_b32_e32 v0, 8, v208
	v_lshl_add_u32 v30, v0, 7, v36
	ds_read_b128 v[30:33], v30 offset:51200
	v_add_f32_e32 v26, 1.0, v26
	v_rcp_f32_e32 v42, v26
	v_mul_f32_e32 v26, 0xbfb8aa3b, v39
	v_exp_f32_e32 v26, v26
	s_waitcnt lgkmcnt(0)
	v_lshlrev_b32_e32 v38, 16, v30
	v_and_b32_e32 v41, 0xffff0000, v30
	v_pk_mul_f32 v[40:41], v[38:39], v[40:41]
	v_add_f32_e32 v26, 1.0, v26
	v_rcp_f32_e32 v43, v26
	v_lshlrev_b32_e32 v30, 16, v27
	v_lshlrev_b32_e32 v0, 11, v0
	v_pk_mul_f32 v[38:39], v[42:43], v[40:41]
	s_nop 0
	v_cvt_pk_bf16_f32 v26, v38, v39
	v_and_b32_e32 v39, 0xffff0000, v27
	v_mul_f32_e32 v27, 0xbfb8aa3b, v30
	v_exp_f32_e32 v27, v27
	v_lshlrev_b32_e32 v38, 16, v31
	v_and_b32_e32 v31, 0xffff0000, v31
	v_pk_mul_f32 v[30:31], v[38:39], v[30:31]
	v_add_f32_e32 v27, 1.0, v27
	v_rcp_f32_e32 v40, v27
	v_mul_f32_e32 v27, 0xbfb8aa3b, v39
	v_exp_f32_e32 v27, v27
	v_lshlrev_b32_e32 v38, 16, v28
	v_and_b32_e32 v39, 0xffff0000, v32
	v_add_f32_e32 v27, 1.0, v27
	v_rcp_f32_e32 v41, v27
	s_nop 0
	v_pk_mul_f32 v[30:31], v[40:41], v[30:31]
	s_nop 0
	v_cvt_pk_bf16_f32 v27, v30, v31
	v_and_b32_e32 v31, 0xffff0000, v28
	v_mul_f32_e32 v28, 0xbfb8aa3b, v38
	v_exp_f32_e32 v28, v28
	v_lshlrev_b32_e32 v30, 16, v32
	v_pk_mul_f32 v[38:39], v[30:31], v[38:39]
	v_lshlrev_b32_e32 v32, 16, v29
	v_add_f32_e32 v28, 1.0, v28
	v_rcp_f32_e32 v40, v28
	v_mul_f32_e32 v28, 0xbfb8aa3b, v31
	v_exp_f32_e32 v28, v28
	s_nop 0
	v_add_f32_e32 v28, 1.0, v28
	v_rcp_f32_e32 v41, v28
	s_nop 0
	v_pk_mul_f32 v[30:31], v[40:41], v[38:39]
	s_nop 0
	v_cvt_pk_bf16_f32 v28, v30, v31
	v_and_b32_e32 v31, 0xffff0000, v29
	v_mul_f32_e32 v29, 0xbfb8aa3b, v32
	v_exp_f32_e32 v29, v29
	v_lshlrev_b32_e32 v30, 16, v33
	v_and_b32_e32 v33, 0xffff0000, v33
	v_pk_mul_f32 v[32:33], v[30:31], v[32:33]
	v_add_f32_e32 v29, 1.0, v29
	v_rcp_f32_e32 v38, v29
	v_mul_f32_e32 v29, 0xbfb8aa3b, v31
	v_exp_f32_e32 v29, v29
	s_nop 0
	v_add_f32_e32 v29, 1.0, v29
	v_rcp_f32_e32 v39, v29
	s_nop 0
	v_pk_mul_f32 v[30:31], v[38:39], v[32:33]
	s_nop 0
	v_cvt_pk_bf16_f32 v29, v30, v31
	v_lshl_add_u64 v[30:31], v[34:35], 0, v[0:1]
	v_lshlrev_b32_e32 v32, 16, v22
	global_store_dwordx4 v[30:31], v[26:29], off
	v_and_b32_e32 v31, 0xffff0000, v22
	v_mul_f32_e32 v22, 0xbfb8aa3b, v32
	v_exp_f32_e32 v22, v22
	v_or_b32_e32 v0, 16, v208
	v_lshl_add_u32 v26, v0, 7, v36
	ds_read_b128 v[26:29], v26 offset:51200
	v_add_f32_e32 v22, 1.0, v22
	v_rcp_f32_e32 v38, v22
	v_mul_f32_e32 v22, 0xbfb8aa3b, v31
	v_exp_f32_e32 v22, v22
	s_waitcnt lgkmcnt(0)
; __device__ __forceinline__ unsigned cvtpk_s(float lo,float hi){f32x2_t v={lo,hi};bf16x2_t b=__builtin_convertvector(v,bf16x2_t);return __builtin_bit_cast(unsigned,b);}
; template<int THRL,bool FIXREF,bool HALFK> __device__ __forceinline__ void attn_unit(float mref,long rowbase,int q0,const bf16*Qh,int PQ,const bf16*__restrict__ Kh_,int PK,const bf16*__restrict__ Vh_,int PV,bf16*Oh,int PO,const bf16*Gh,int PG,u32x4(&okeep)[4],int omode,float lam,float oml,const float ...
;     ...
;       for(int i=0;i<4;++i){const int row=i*8+(lane>>3),ch=lane&7; u32x4 v=*(const u32x4*)(stg+row*64+ch*8);
;         #pragma unroll
;         for(int k=0;k<4;++k){ const float g0=__uint_as_float(gv[i][k]<<16),g1=__uint_as_float(gv[i][k]&0xffff0000u),o0=__uint_as_float(v[k]<<16),o1=__uint_as_float(v[k]&0xffff0000u);
;           v[k]=cvtpk_s(o0*g0*__builtin_amdgcn_rcpf(1.f+__builtin_amdgcn_exp2f(-1.4426950408889634f*g0)),o1*g1*__builtin_amdgcn_rcpf(1.f+__builtin_amdgcn_exp2f(-1.4426950408889634f*g1))); }
;         ATTN_STORE16(Ow+(long)row*PO+ch*8,v);} }
	v_lshlrev_b32_e32 v30, 16, v26
	v_and_b32_e32 v33, 0xffff0000, v26
	v_pk_mul_f32 v[32:33], v[30:31], v[32:33]
	v_add_f32_e32 v22, 1.0, v22
	v_rcp_f32_e32 v39, v22
	v_lshlrev_b32_e32 v26, 16, v23
	v_lshlrev_b32_e32 v0, 11, v0
	v_pk_mul_f32 v[30:31], v[38:39], v[32:33]
	s_nop 0
	v_cvt_pk_bf16_f32 v22, v30, v31
	v_and_b32_e32 v31, 0xffff0000, v23
	v_mul_f32_e32 v23, 0xbfb8aa3b, v26
	v_exp_f32_e32 v23, v23
	v_lshlrev_b32_e32 v30, 16, v27
	v_and_b32_e32 v27, 0xffff0000, v27
	v_pk_mul_f32 v[26:27], v[30:31], v[26:27]
	v_add_f32_e32 v23, 1.0, v23
	v_rcp_f32_e32 v32, v23
	v_mul_f32_e32 v23, 0xbfb8aa3b, v31
	v_exp_f32_e32 v23, v23
	v_lshlrev_b32_e32 v30, 16, v24
	v_and_b32_e32 v31, 0xffff0000, v28
	v_add_f32_e32 v23, 1.0, v23
	v_rcp_f32_e32 v33, v23
	s_nop 0
	v_pk_mul_f32 v[26:27], v[32:33], v[26:27]
	s_nop 0
	v_cvt_pk_bf16_f32 v23, v26, v27
	v_and_b32_e32 v27, 0xffff0000, v24
	v_mul_f32_e32 v24, 0xbfb8aa3b, v30
	v_exp_f32_e32 v24, v24
	v_lshlrev_b32_e32 v26, 16, v28
	v_pk_mul_f32 v[30:31], v[26:27], v[30:31]
	v_lshlrev_b32_e32 v28, 16, v25
	v_add_f32_e32 v24, 1.0, v24
	v_rcp_f32_e32 v32, v24
	v_mul_f32_e32 v24, 0xbfb8aa3b, v27
	v_exp_f32_e32 v24, v24
	s_nop 0
	v_add_f32_e32 v24, 1.0, v24
	v_rcp_f32_e32 v33, v24
	s_nop 0
	v_pk_mul_f32 v[26:27], v[32:33], v[30:31]
	s_nop 0
	v_cvt_pk_bf16_f32 v24, v26, v27
	v_and_b32_e32 v27, 0xffff0000, v25
	v_mul_f32_e32 v25, 0xbfb8aa3b, v28
	v_exp_f32_e32 v25, v25
	v_lshlrev_b32_e32 v26, 16, v29
	v_and_b32_e32 v29, 0xffff0000, v29
	v_pk_mul_f32 v[28:29], v[26:27], v[28:29]
	v_add_f32_e32 v25, 1.0, v25
	v_rcp_f32_e32 v30, v25
	v_mul_f32_e32 v25, 0xbfb8aa3b, v27
	v_exp_f32_e32 v25, v25
	s_nop 0
	v_add_f32_e32 v25, 1.0, v25
	v_rcp_f32_e32 v31, v25
	s_nop 0
	v_pk_mul_f32 v[26:27], v[30:31], v[28:29]
	s_nop 0
	v_cvt_pk_bf16_f32 v25, v26, v27
	v_lshl_add_u64 v[26:27], v[34:35], 0, v[0:1]
	v_lshlrev_b32_e32 v28, 16, v18
	global_store_dwordx4 v[26:27], v[22:25], off
	v_and_b32_e32 v27, 0xffff0000, v18
	v_mul_f32_e32 v18, 0xbfb8aa3b, v28
	v_exp_f32_e32 v18, v18
	v_or_b32_e32 v0, 24, v208
	v_lshl_add_u32 v22, v0, 7, v36
	ds_read_b128 v[22:25], v22 offset:51200
	v_add_f32_e32 v18, 1.0, v18
	v_rcp_f32_e32 v30, v18
	v_mul_f32_e32 v18, 0xbfb8aa3b, v27
	v_exp_f32_e32 v18, v18
	s_waitcnt lgkmcnt(0)
	v_lshlrev_b32_e32 v26, 16, v22
	v_and_b32_e32 v29, 0xffff0000, v22
	v_pk_mul_f32 v[28:29], v[26:27], v[28:29]
	v_add_f32_e32 v18, 1.0, v18
	v_rcp_f32_e32 v31, v18
	v_lshlrev_b32_e32 v22, 16, v19
	v_lshlrev_b32_e32 v0, 11, v0
	v_pk_mul_f32 v[26:27], v[30:31], v[28:29]
	s_nop 0
	v_cvt_pk_bf16_f32 v18, v26, v27
	v_and_b32_e32 v27, 0xffff0000, v19
	v_mul_f32_e32 v19, 0xbfb8aa3b, v22
	v_exp_f32_e32 v19, v19
	v_lshlrev_b32_e32 v26, 16, v23
	v_and_b32_e32 v23, 0xffff0000, v23
	v_pk_mul_f32 v[22:23], v[26:27], v[22:23]
	v_add_f32_e32 v19, 1.0, v19
	v_rcp_f32_e32 v28, v19
	v_mul_f32_e32 v19, 0xbfb8aa3b, v27
	v_exp_f32_e32 v19, v19
	v_lshlrev_b32_e32 v26, 16, v20
	v_and_b32_e32 v27, 0xffff0000, v24
	v_add_f32_e32 v19, 1.0, v19
	v_rcp_f32_e32 v29, v19
	s_nop 0
	v_pk_mul_f32 v[22:23], v[28:29], v[22:23]
	s_nop 0
	v_cvt_pk_bf16_f32 v19, v22, v23
	v_and_b32_e32 v23, 0xffff0000, v20
	v_mul_f32_e32 v20, 0xbfb8aa3b, v26
	v_exp_f32_e32 v20, v20
	v_lshlrev_b32_e32 v22, 16, v24
	v_pk_mul_f32 v[26:27], v[22:23], v[26:27]
	v_lshlrev_b32_e32 v24, 16, v21
	v_add_f32_e32 v20, 1.0, v20
	v_rcp_f32_e32 v28, v20
	v_mul_f32_e32 v20, 0xbfb8aa3b, v23
	v_exp_f32_e32 v20, v20
	s_nop 0
	v_add_f32_e32 v20, 1.0, v20
	v_rcp_f32_e32 v29, v20
	s_nop 0
	v_pk_mul_f32 v[22:23], v[28:29], v[26:27]
	s_nop 0
	v_cvt_pk_bf16_f32 v20, v22, v23
	v_and_b32_e32 v23, 0xffff0000, v21
	v_mul_f32_e32 v21, 0xbfb8aa3b, v24
	v_exp_f32_e32 v21, v21
	v_lshlrev_b32_e32 v22, 16, v25
	v_and_b32_e32 v25, 0xffff0000, v25
	v_pk_mul_f32 v[24:25], v[22:23], v[24:25]
	v_add_f32_e32 v21, 1.0, v21
	v_rcp_f32_e32 v26, v21
	v_mul_f32_e32 v21, 0xbfb8aa3b, v23
	v_exp_f32_e32 v21, v21
	s_nop 0
	v_add_f32_e32 v21, 1.0, v21
	v_rcp_f32_e32 v27, v21
	s_nop 0
	v_pk_mul_f32 v[22:23], v[26:27], v[24:25]
	s_nop 0
	v_cvt_pk_bf16_f32 v21, v22, v23
	v_lshl_add_u64 v[22:23], v[34:35], 0, v[0:1]
	global_store_dwordx4 v[22:23], v[18:21], off
